# hand-written attention phase: LDS-DMA K/V staging 2 tiles ahead, 4-slot rings, interleaved MFMA/softmax schedule
# speedup vs baseline: 1.3907x; 1.3907x over previous
; __device__ __forceinline__ void attn_item(const bf16_t* __restrict__ Qb, const bf16_t* __restrict__ Kn, const bf16_t* __restrict__ Kr, const bf16_t* __restrict__ Vh,
;                                           const float* __restrict__ csq, bf16_t* __restrict__ Ob, int seq, char* lds) {
;   int tid_ = threadIdx.x; asm volatile("" : "+v"(tid_));
;   const int tid = tid_, wid = tid >> 6, lane = tid & 63, r32 = lane & 31, hi = lane >> 5;
;   bf16_t* V_lds = (bf16_t*)lds; bf16_t* K_lds = (bf16_t*)(lds + 3 * SLOT);
;   float* ws = (float*)(lds + 6 * SLOT) + wid * 64; float* li_l = ws; float* al_l = ws + 32;
;   float mhat = 0.f, l_reg = 0; f32x16 o[2] = {}; bf16x8 qr[6]; f32x16 negm = f32x16{};
;   const bf16_t* Qw = Qb + (long)(wid * QBLK + r32) * 1792 + hi * 8;
; #pragma unroll
;   for (int d0 = 0; d0 < 6; ++d0) qr[d0] = *reinterpret_cast<const bf16x8*>(Qw + d0 * 16);
;   { const float* cp = csq + (long)(wid * QBLK + r32) * 32 + hi * 8;
;     const f32x4 c0 = *(const f32x4*)cp, c1 = *(const f32x4*)(cp + 4), s0 = *(const f32x4*)(cp + 16), s1 = *(const f32x4*)(cp + 20);
;     float cc[8] = {c0[0], c0[1], c0[2], c0[3], c1[0], c1[1], c1[2], c1[3]}, ss[8] = {s0[0], s0[1], s0[2], s0[3], s1[0], s1[1], s1[2], s1[3]};
;     bf16x8 n4, n5;
; #pragma unroll
;     for (int e = 0; e < 8; ++e) { const float x1 = bf2f((unsigned short)qr[4][e]), x2 = bf2f((unsigned short)qr[5][e]);
;       n4[e] = (short)f2bf(x1 * cc[e] - x2 * ss[e]); n5[e] = (short)f2bf(x1 * ss[e] + x2 * cc[e]); }
;     qr[4] = n4; qr[5] = n5; }
;   const int sr = tid >> 3, sc = (tid & 7) * 8, vst0 = v_st(sr, sc);
;   const int rr_ = (tid & 255) >> 2, rc_ = (tid & 3) * 8;
;   const int vb0 = (int)(uintptr_t)V_lds + v_rd_base(lane);
; __global__ void __launch_bounds__(512, 2) mega(Args a_unused) {
;     ...
;             if constexpr (PHMASK & 512) for (int rep = 0; rep <= DUP_ATT; ++rep) for (int it = C.vcu; it < NB * NH * (SEQ / 256); it += C.G) { const int bh = it >> 5, qb = it & 31; const int b = bh >> 3, hh = bh & 7;
;                 const bf16_t* qkvb = Hb + (size_t)b * SEQ * NQKV;
;                 att::attn_item(qkvb + (size_t)(qb * 256) * NQKV + hh * 96, qkvb + 768 + hh * 128, KPE + (size_t)b * SEQ * 32, qkvb + 768 + hh * 128 + 64,
;                                CS + (size_t)(b * SEQ + qb * 256) * 32, YB + ((size_t)(b * SEQ + qb * 256)) * DM + hh * 64, SEQ, (char*)C.lds); }
.LBB0_666:
	s_mov_b64 s[8:9], s[84:85]
	s_load_dword s0, s[8:9], 0x120
	s_add_i32 s24, s63, 5
	s_waitcnt lgkmcnt(0)
	s_cmp_lt_i32 s24, s0
	s_cbranch_scc1 .LBB0_707
	s_load_dword s0, s[8:9], 0x124
	s_waitcnt lgkmcnt(0)
	s_cmp_ge_i32 s24, s0
	s_cbranch_scc1 .LBB0_707
	v_readlane_b32 s0, v255, 13
	v_readlane_b32 s1, v255, 14
	v_mov_b32_e32 v1, v180
	s_andn2_b64 vcc, exec, s[0:1]
	s_cbranch_vccnz .LBB0_707
	s_load_dwordx4 s[12:15], s[8:9], 0x110
	v_readlane_b32 s28, v255, 49
	v_and_b32_e32 v1, 63, v180
	v_lshrrev_b32_e32 v177, 6, v180
	s_nop 0
	v_readfirstlane_b32 s29, v177
	v_and_b32_e32 v178, 31, v1
	v_lshrrev_b32_e32 v179, 5, v1
	v_and_b32_e32 v213, 7, v178
	v_lshlrev_b32_e32 v214, 8, v178
	v_add_u32_e32 v214, 65536, v214
	v_or_b32_e32 v215, 0, v179
	v_xor_b32_e32 v215, v215, v213
	v_lshl_add_u32 v140, v215, 4, v214
	v_or_b32_e32 v215, 2, v179
	v_xor_b32_e32 v215, v215, v213
	v_lshl_add_u32 v141, v215, 4, v214
	v_or_b32_e32 v215, 4, v179
	v_xor_b32_e32 v215, v215, v213
	v_lshl_add_u32 v142, v215, 4, v214
	v_or_b32_e32 v215, 6, v179
	v_xor_b32_e32 v215, v215, v213
	v_lshl_add_u32 v143, v215, 4, v214
	v_or_b32_e32 v215, 8, v179
	v_xor_b32_e32 v215, v215, v213
	v_lshl_add_u32 v144, v215, 4, v214
	v_or_b32_e32 v215, 10, v179
	v_xor_b32_e32 v215, v215, v213
	v_lshl_add_u32 v145, v215, 4, v214
	v_and_b32_e32 v213, 3, v1
	v_lshlrev_b32_e32 v213, 3, v213
	v_bfe_u32 v214, v1, 2, 2
	v_lshl_or_b32 v213, v214, 6, v213
	v_bfe_u32 v214, v1, 4, 1
	v_lshl_or_b32 v213, v214, 5, v213
	v_lshl_or_b32 v150, v179, 8, v213
	s_lshl_b32 s0, s29, 8
	s_add_i32 s0, s0, 131072
	v_lshl_add_u32 v175, v178, 2, s0
	v_lshl_add_u32 v176, v179, 4, s0
	s_lshl_b32 s6, s29, 11
	s_mov_b32 s7, s6
	s_add_i32 s6, s6, 65536
	v_and_b32_e32 v213, 15, v1
	v_lshrrev_b32_e32 v214, 4, v1
	v_and_b32_e32 v215, 7, v213
	v_or_b32_e32 v216, 0, v214
	v_xor_b32_e32 v216, v215, v216
	v_cmp_gt_u32_e32 vcc, 4, v216
	v_cmp_gt_u32_e64 s[0:1], 8, v213
	s_or_b64 s[20:21], vcc, s[0:1]
	v_or_b32_e32 v216, 4, v214
	v_xor_b32_e32 v216, v215, v216
	v_cmp_gt_u32_e32 vcc, 4, v216
	v_cmp_gt_u32_e64 s[0:1], 8, v213
	s_or_b64 s[22:23], vcc, s[0:1]
	s_movk_i32 s25, 0x7fff
	s_waitcnt lgkmcnt(0)
	s_mov_b32 s9, 0
.Lat_item:
	s_lshr_b32 s0, s28, 5
	s_and_b32 s1, s28, 31
	s_lshr_b32 s2, s0, 3
	s_and_b32 s0, s0, 7
	s_mul_i32 s10, s2, 0x1c00000
	s_add_u32 s16, s14, 0xd600000
	s_addc_u32 s17, s15, 0
	s_add_u32 s16, s16, s10
	s_addc_u32 s17, s17, 0
	s_mul_i32 s11, s1, 0xe0000
	s_mul_i32 s30, s0, 192
	s_add_i32 s11, s11, s30
	s_add_u32 s16, s16, s11
	s_addc_u32 s17, s17, 0
	s_lshl_b32 s30, s2, 13
	s_lshl_b32 s31, s1, 8
	s_add_i32 s30, s30, s31
	s_lshl_b32 s31, s30, 7
	s_add_u32 s18, s14, 0x5100000
	s_addc_u32 s19, s15, 0
	s_add_u32 s18, s18, s31
	s_addc_u32 s19, s19, 0
	s_lshl_b32 s31, s30, 11
	s_lshl_b32 s11, s0, 7
	s_add_i32 s31, s31, s11
	s_add_u32 s26, s12, s31
	s_addc_u32 s27, s13, 0
	s_lshl_b32 s11, s0, 8
	s_add_i32 s10, s10, s11
	s_add_i32 s10, s10, 0xd600600
	s_lshl_b32 s11, s2, 19
	s_add_i32 s11, s11, 0x1de00000
	v_and_b32_e32 v1, 63, v180
	v_and_b32_e32 v178, 31, v1
	v_lshrrev_b32_e32 v179, 5, v1
	s_lshl_b32 s30, s29, 5
	v_add_u32_e32 v213, s30, v178
	s_movk_i32 s31, 0xe00
	v_mul_lo_u32 v214, v213, s31
	v_lshl_add_u32 v214, v179, 4, v214
	v_lshlrev_b32_e32 v215, 7, v213
	v_lshl_add_u32 v215, v179, 5, v215
	s_barrier
	global_load_dwordx4 v[114:117], v214, s[16:17] offset:0
	global_load_dwordx4 v[118:121], v214, s[16:17] offset:32
	global_load_dwordx4 v[122:125], v214, s[16:17] offset:64
	global_load_dwordx4 v[126:129], v214, s[16:17] offset:96
	global_load_dwordx4 v[130:133], v214, s[16:17] offset:128
	global_load_dwordx4 v[134:137], v214, s[16:17] offset:160
	global_load_dwordx4 v[34:37], v215, s[18:19]
	global_load_dwordx4 v[38:41], v215, s[18:19] offset:16
	global_load_dwordx4 v[42:45], v215, s[18:19] offset:64
	global_load_dwordx4 v[46:49], v215, s[18:19] offset:80
	v_and_b32_e32 v213, 15, v1
	v_lshrrev_b32_e32 v214, 4, v1
	v_and_b32_e32 v215, 7, v213
	v_cmp_gt_u32_e32 vcc, 8, v213
	v_mov_b32_e32 v216, s11
	v_mov_b32_e32 v217, s10
	s_nop 0
	v_cndmask_b32_e32 v216, v216, v217, vcc
	v_mov_b32_e32 v217, 0x1000
	v_mov_b32_e32 v148, 0x38000
	v_cndmask_b32_e32 v148, v217, v148, vcc
	v_mov_b32_e32 v217, 64
	v_mov_b32_e32 v177, 0xe00
	v_cndmask_b32_e32 v217, v217, v177, vcc
	s_lshl_b32 s30, s29, 3
	v_or_b32_e32 v177, 0, v214
	v_xor_b32_e32 v1, v215, v177
	v_add_u32_e32 v177, s30, v177
	v_mul_lo_u32 v177, v177, v217
	v_lshl_add_u32 v177, v1, 4, v177
	v_add_u32_e32 v146, v177, v216
	v_or_b32_e32 v177, 4, v214
	v_xor_b32_e32 v1, v215, v177
	v_add_u32_e32 v177, s30, v177
	v_mul_lo_u32 v177, v177, v217
	v_lshl_add_u32 v177, v1, 4, v177
	v_add_u32_e32 v147, v177, v216
	v_and_b32_e32 v1, 63, v180
	v_bfe_u32 v213, v1, 2, 3
	v_add_u32_e32 v213, s30, v213
	v_and_b32_e32 v214, 4, v213
	v_and_b32_e32 v215, 8, v213
	v_and_b32_e32 v213, 0xfffffff3, v213
	v_lshl_or_b32 v213, v214, 1, v213
	v_lshrrev_b32_e32 v215, 1, v215
	v_or_b32_e32 v213, v213, v215
	s_movk_i32 s31, 0xe00
	v_mul_lo_u32 v213, v213, s31
	v_and_b32_e32 v214, 3, v1
	v_lshl_add_u32 v213, v214, 4, v213
	v_lshrrev_b32_e32 v214, 5, v1
	v_lshl_add_u32 v213, v214, 6, v213
	s_add_i32 s31, s10, 128
	v_add_u32_e32 v149, s31, v213
	s_cmp_lt_u32 s29, 4
	s_cbranch_scc1 .Lat_prio
	s_setprio 1
; __device__ __forceinline__ unsigned f2bf(float f) { unsigned u = __builtin_bit_cast(unsigned, f); return (u + 0x7fffu + ((u >> 16) & 1u)) >> 16; }
; __device__ __forceinline__ int v_st(int k, int c) { const int kk = (k & ~0xC) | ((k & 4) << 1) | ((k & 8) >> 1); return ((kk >> 3) * 4 + (c >> 5)) * 512 + ((kk & 7) * 32 + (c & 31)) * 2; }
; __device__ __forceinline__ int v_rd_base(int lane) { return ((lane & 3) << 3) | (((lane >> 2) & 3) << 6) | (((lane >> 4) & 1) << 5) | (((lane >> 5) & 1) << 8); }
; #define SWAIT() asm volatile("s_waitcnt vmcnt(0)" ::: "memory")
; __device__ __forceinline__ void attn_item(const bf16_t* __restrict__ Qb, const bf16_t* __restrict__ Kn, const bf16_t* __restrict__ Kr, const bf16_t* __restrict__ Vh,
;                                           const float* __restrict__ csq, bf16_t* __restrict__ Ob, int seq, char* lds) {
;     ...
;   const bf16_t* Qw = Qb + (long)(wid * QBLK + r32) * 1792 + hi * 8;
; #pragma unroll
;   for (int d0 = 0; d0 < 6; ++d0) qr[d0] = *reinterpret_cast<const bf16x8*>(Qw + d0 * 16);
;   { const float* cp = csq + (long)(wid * QBLK + r32) * 32 + hi * 8;
;     const f32x4 c0 = *(const f32x4*)cp, c1 = *(const f32x4*)(cp + 4), s0 = *(const f32x4*)(cp + 16), s1 = *(const f32x4*)(cp + 20);
;     float cc[8] = {c0[0], c0[1], c0[2], c0[3], c1[0], c1[1], c1[2], c1[3]}, ss[8] = {s0[0], s0[1], s0[2], s0[3], s1[0], s1[1], s1[2], s1[3]};
;     bf16x8 n4, n5;
; #pragma unroll
;     for (int e = 0; e < 8; ++e) { const float x1 = bf2f((unsigned short)qr[4][e]), x2 = bf2f((unsigned short)qr[5][e]);
;       n4[e] = (short)f2bf(x1 * cc[e] - x2 * ss[e]); n5[e] = (short)f2bf(x1 * ss[e] + x2 * cc[e]); }
;     qr[4] = n4; qr[5] = n5; }
;   const int sr = tid >> 3, sc = (tid & 7) * 8, vst0 = v_st(sr, sc);
;   const int rr_ = (tid & 255) >> 2, rc_ = (tid & 3) * 8;
;   const int vb0 = (int)(uintptr_t)V_lds + v_rd_base(lane);
;   struct { bf16x8 vs, kn, kr; } sr_[1];
;     ...
;   f32x16 pA0, pA1, pB0, pB1; float alA, alB; bf16x8 pa0, pa1, pa2, pa3; const int NT = seq / KVBLK;
;   int sp = 0, scu = 0, sn = SLOT;
;     ...
;   if (__builtin_amdgcn_readfirstlane(wid) >= 4) __builtin_amdgcn_s_setprio(1);
;   __syncthreads();
;   SLOAD(0, 0); SWAIT(); SWRITE(0, 0); __syncthreads();
;   qkt(pA0, pA1, K_lds, qr, negm, r32, hi); partialSM<true>(pA0, pA1, mhat, negm, alA);
;   SLOAD(0, KVBLK); SWAIT(); SWRITE(SLOT, 0); __syncthreads();
.Lat_prio:
	s_add_i32 m0, s6, 0
	s_mov_b64 exec, s[20:21]
	global_load_lds_dwordx4 v146, s[14:15]
	s_add_i32 m0, s6, 1024
	s_mov_b64 exec, s[22:23]
	global_load_lds_dwordx4 v147, s[14:15]
	s_mov_b64 exec, -1
	v_add_u32_e32 v146, v146, v148
	v_add_u32_e32 v147, v147, v148
	s_add_i32 m0, s6, 16384
	s_mov_b64 exec, s[20:21]
	global_load_lds_dwordx4 v146, s[14:15]
	s_add_i32 m0, s6, 17408
	s_mov_b64 exec, s[22:23]
	global_load_lds_dwordx4 v147, s[14:15]
	s_mov_b64 exec, -1
	v_add_u32_e32 v146, v146, v148
	v_add_u32_e32 v147, v147, v148
	s_add_i32 m0, s6, 32768
	s_mov_b64 exec, s[20:21]
	global_load_lds_dwordx4 v146, s[14:15]
	s_add_i32 m0, s6, 33792
	s_mov_b64 exec, s[22:23]
	global_load_lds_dwordx4 v147, s[14:15]
	s_mov_b64 exec, -1
	v_add_u32_e32 v146, v146, v148
	v_add_u32_e32 v147, v147, v148
	s_add_i32 m0, s7, 0
	s_nop 0
	global_load_lds_dwordx4 v149, s[14:15]
	v_add_u32_e32 v149, 0x38000, v149
	s_add_i32 m0, s6, 49152
	s_mov_b64 exec, s[20:21]
	global_load_lds_dwordx4 v146, s[14:15]
	s_add_i32 m0, s6, 50176
	s_mov_b64 exec, s[22:23]
	global_load_lds_dwordx4 v147, s[14:15]
	s_mov_b64 exec, -1
	v_add_u32_e32 v146, v146, v148
	v_add_u32_e32 v147, v147, v148
	s_add_i32 m0, s7, 16384
	s_nop 0
	global_load_lds_dwordx4 v149, s[14:15]
	v_add_u32_e32 v149, 0x38000, v149
	v_mov_b64_e32 v[2:3], 0
	v_mov_b64_e32 v[4:5], 0
	v_mov_b64_e32 v[6:7], 0
	v_mov_b64_e32 v[8:9], 0
	v_mov_b64_e32 v[10:11], 0
	v_mov_b64_e32 v[12:13], 0
	v_mov_b64_e32 v[14:15], 0
	v_mov_b64_e32 v[16:17], 0
	v_mov_b64_e32 v[18:19], 0
	v_mov_b64_e32 v[20:21], 0
	v_mov_b64_e32 v[22:23], 0
	v_mov_b64_e32 v[24:25], 0
	v_mov_b64_e32 v[26:27], 0
	v_mov_b64_e32 v[28:29], 0
	v_mov_b64_e32 v[30:31], 0
	v_mov_b64_e32 v[32:33], 0
	v_mov_b32_e32 v174, 0
	s_waitcnt vmcnt(10)
	v_lshlrev_b32_e32 v66, 16, v130
	v_and_b32_e32 v67, 0xffff0000, v130
	v_lshlrev_b32_e32 v68, 16, v131
	v_and_b32_e32 v69, 0xffff0000, v131
	v_lshlrev_b32_e32 v70, 16, v132
	v_and_b32_e32 v71, 0xffff0000, v132
	v_lshlrev_b32_e32 v72, 16, v133
	v_and_b32_e32 v73, 0xffff0000, v133
	v_lshlrev_b32_e32 v74, 16, v134
	v_and_b32_e32 v75, 0xffff0000, v134
	v_lshlrev_b32_e32 v76, 16, v135
	v_and_b32_e32 v77, 0xffff0000, v135
	v_lshlrev_b32_e32 v78, 16, v136
	v_and_b32_e32 v79, 0xffff0000, v136
	v_lshlrev_b32_e32 v80, 16, v137
	v_and_b32_e32 v81, 0xffff0000, v137
	v_mul_f32_e32 v82, v74, v42
	v_mul_f32_e32 v90, v66, v42
	v_mul_f32_e32 v83, v75, v43
	v_mul_f32_e32 v91, v67, v43
	v_mul_f32_e32 v84, v76, v44
	v_mul_f32_e32 v92, v68, v44
	v_mul_f32_e32 v85, v77, v45
	v_mul_f32_e32 v93, v69, v45
	v_mul_f32_e32 v86, v78, v46
	v_mul_f32_e32 v94, v70, v46
	v_mul_f32_e32 v87, v79, v47
	v_mul_f32_e32 v95, v71, v47
	v_mul_f32_e32 v88, v80, v48
	v_mul_f32_e32 v96, v72, v48
	v_mul_f32_e32 v89, v81, v49
	v_mul_f32_e32 v97, v73, v49
	v_fma_f32 v82, v66, v34, -v82
	v_fma_f32 v90, v74, v34, v90
	v_fma_f32 v83, v67, v35, -v83
	v_fma_f32 v91, v75, v35, v91
	v_fma_f32 v84, v68, v36, -v84
	v_fma_f32 v92, v76, v36, v92
	v_fma_f32 v85, v69, v37, -v85
	v_fma_f32 v93, v77, v37, v93
	v_fma_f32 v86, v70, v38, -v86
	v_fma_f32 v94, v78, v38, v94
	v_fma_f32 v87, v71, v39, -v87
	v_fma_f32 v95, v79, v39, v95
	v_fma_f32 v88, v72, v40, -v88
	v_fma_f32 v96, v80, v40, v96
	v_fma_f32 v89, v73, v41, -v89
	v_fma_f32 v97, v81, v41, v97
	v_cvt_pk_bf16_f32 v130, v82, v83
	v_cvt_pk_bf16_f32 v134, v90, v91
	v_cvt_pk_bf16_f32 v131, v84, v85
	v_cvt_pk_bf16_f32 v135, v92, v93
	v_cvt_pk_bf16_f32 v132, v86, v87
	v_cvt_pk_bf16_f32 v136, v94, v95
	v_cvt_pk_bf16_f32 v133, v88, v89
	v_cvt_pk_bf16_f32 v137, v96, v97
	s_waitcnt vmcnt(8)
	s_barrier
	ds_read_b128 v[182:185], v140 offset:0
	ds_read_b128 v[186:189], v140 offset:8192
	ds_read_b128 v[190:193], v141 offset:0
	ds_read_b128 v[194:197], v141 offset:8192
	ds_read_b128 v[198:201], v142 offset:0
	ds_read_b128 v[202:205], v142 offset:8192
	ds_read_b128 v[206:209], v143 offset:0
	ds_read_b128 v[210:213], v143 offset:8192
	s_waitcnt lgkmcnt(7)
	v_mfma_f32_32x32x16_bf16 v[34:49], v[182:185], v[114:117], 0
	ds_read_b128 v[182:185], v144 offset:0
	s_waitcnt lgkmcnt(7)
	v_mfma_f32_32x32x16_bf16 v[50:65], v[186:189], v[114:117], 0
	ds_read_b128 v[186:189], v144 offset:8192
	s_waitcnt lgkmcnt(7)
	v_mfma_f32_32x32x16_bf16 v[34:49], v[190:193], v[118:121], v[34:49]
	ds_read_b128 v[190:193], v145 offset:0
	s_waitcnt lgkmcnt(7)
	v_mfma_f32_32x32x16_bf16 v[50:65], v[194:197], v[118:121], v[50:65]
	ds_read_b128 v[194:197], v145 offset:8192
	s_waitcnt lgkmcnt(7)
	v_mfma_f32_32x32x16_bf16 v[34:49], v[198:201], v[122:125], v[34:49]
	s_waitcnt lgkmcnt(6)
	v_mfma_f32_32x32x16_bf16 v[50:65], v[202:205], v[122:125], v[50:65]
	s_waitcnt lgkmcnt(5)
	v_mfma_f32_32x32x16_bf16 v[34:49], v[206:209], v[126:129], v[34:49]
	s_waitcnt lgkmcnt(4)
	v_mfma_f32_32x32x16_bf16 v[50:65], v[210:213], v[126:129], v[50:65]
	s_waitcnt lgkmcnt(3)
	v_mfma_f32_32x32x16_bf16 v[34:49], v[182:185], v[130:133], v[34:49]
	s_waitcnt lgkmcnt(2)
	v_mfma_f32_32x32x16_bf16 v[50:65], v[186:189], v[130:133], v[50:65]
	s_waitcnt lgkmcnt(1)
	v_mfma_f32_32x32x16_bf16 v[34:49], v[190:193], v[134:137], v[34:49]
	s_waitcnt lgkmcnt(0)
; template <bool FIRST> __device__ __forceinline__ void partialSM(f32x16& p0, f32x16& p1, float& mhat, f32x16& negm, float& alpha) {
;   float pa = fmaxf(fmaxf(p0[0], p0[1]), p1[0]), pb = fmaxf(fmaxf(p0[2], p0[3]), p1[1]); pa = fmaxf(fmaxf(pa, p1[2]), p1[3]);
; #pragma unroll
;   for (int r = 4; r < 16; r += 4) { pa = fmaxf(fmaxf(pa, p0[r]), p0[r + 1]); pb = fmaxf(fmaxf(pb, p0[r + 2]), p0[r + 3]); pa = fmaxf(fmaxf(pa, p1[r]), p1[r + 1]); pb = fmaxf(fmaxf(pb, p1[r + 2]), p1[r + 3]); }
;   float pmax = fmaxf(pa, pb);
;   { auto rr = __builtin_amdgcn_permlane32_swap(__float_as_uint(pmax), __float_as_uint(pmax), false, false);
;     pmax = fmaxf(__uint_as_float(rr[0]), __uint_as_float(rr[1])); }
;   if (!FIRST && __builtin_expect(__all(pmax <= THRL), 1)) { alpha = 1.f; }
;   else { const float d = FIRST ? pmax : fmaxf(pmax, 0.f); mhat += d; alpha = FIRST ? 1.f : __builtin_amdgcn_exp2f(-d);
; #pragma unroll
;     for (int r = 0; r < 16; ++r) { p0[r] -= d; p1[r] -= d; }
; #pragma unroll
;     for (int r = 0; r < 16; ++r) negm[r] = -mhat; }
; #pragma unroll
;   for (int r = 0; r < 16; ++r) p0[r] = __builtin_amdgcn_exp2f(p0[r]);
; }
	v_mfma_f32_32x32x16_bf16 v[50:65], v[194:197], v[134:137], v[50:65]
	s_nop 9
	v_max3_f32 v177, v34, v35, v36
	v_max3_f32 v178, v37, v38, v39
	v_max3_f32 v177, v177, v40, v41
	v_max3_f32 v178, v178, v42, v43
	v_max3_f32 v177, v177, v44, v45
	v_max3_f32 v178, v178, v46, v47
	v_max3_f32 v177, v177, v48, v49
	v_max3_f32 v178, v178, v50, v51
	v_max3_f32 v177, v177, v52, v53
	v_max3_f32 v178, v178, v54, v55
	v_max3_f32 v177, v177, v56, v57
	v_max3_f32 v178, v178, v58, v59
	v_max3_f32 v177, v177, v60, v61
	v_max3_f32 v178, v178, v62, v63
	v_max3_f32 v177, v177, v64, v65
	v_max_f32_e32 v177, v177, v178
	v_mov_b32_e32 v178, v177
	s_nop 1
	v_permlane32_swap_b32_e32 v177, v178
	v_max_f32_e32 v177, v177, v178
	v_mov_b32_e32 v151, v177
	v_sub_f32_e32 v34, v34, v177
	v_sub_f32_e32 v35, v35, v177
	v_sub_f32_e32 v36, v36, v177
	v_sub_f32_e32 v37, v37, v177
	v_sub_f32_e32 v38, v38, v177
	v_sub_f32_e32 v39, v39, v177
	v_sub_f32_e32 v40, v40, v177
	v_sub_f32_e32 v41, v41, v177
	v_sub_f32_e32 v42, v42, v177
	v_sub_f32_e32 v43, v43, v177
	v_sub_f32_e32 v44, v44, v177
	v_sub_f32_e32 v45, v45, v177
	v_sub_f32_e32 v46, v46, v177
	v_sub_f32_e32 v47, v47, v177
	v_sub_f32_e32 v48, v48, v177
	v_sub_f32_e32 v49, v49, v177
	v_sub_f32_e32 v50, v50, v177
	v_sub_f32_e32 v51, v51, v177
	v_sub_f32_e32 v52, v52, v177
	v_sub_f32_e32 v53, v53, v177
	v_sub_f32_e32 v54, v54, v177
	v_sub_f32_e32 v55, v55, v177
	v_sub_f32_e32 v56, v56, v177
	v_sub_f32_e32 v57, v57, v177
	v_sub_f32_e32 v58, v58, v177
	v_sub_f32_e32 v59, v59, v177
	v_sub_f32_e32 v60, v60, v177
	v_sub_f32_e32 v61, v61, v177
	v_sub_f32_e32 v62, v62, v177
	v_sub_f32_e32 v63, v63, v177
	v_sub_f32_e32 v64, v64, v177
	v_sub_f32_e32 v65, v65, v177
	v_xor_b32_e32 v98, 0x80000000, v151
	v_mov_b32_e32 v99, v98
	v_mov_b32_e32 v100, v98
	v_mov_b32_e32 v101, v98
	v_mov_b32_e32 v102, v98
	v_mov_b32_e32 v103, v98
	v_mov_b32_e32 v104, v98
	v_mov_b32_e32 v105, v98
	v_mov_b32_e32 v106, v98
	v_mov_b32_e32 v107, v98
	v_mov_b32_e32 v108, v98
	v_mov_b32_e32 v109, v98
	v_mov_b32_e32 v110, v98
	v_mov_b32_e32 v111, v98
	v_mov_b32_e32 v112, v98
	v_mov_b32_e32 v113, v98
	v_exp_f32_e32 v34, v34
	v_exp_f32_e32 v35, v35
	v_exp_f32_e32 v36, v36
	v_exp_f32_e32 v37, v37
	v_exp_f32_e32 v38, v38
	v_exp_f32_e32 v39, v39
	v_exp_f32_e32 v40, v40
	v_exp_f32_e32 v41, v41
	v_exp_f32_e32 v42, v42
	v_exp_f32_e32 v43, v43
	v_exp_f32_e32 v44, v44
	v_exp_f32_e32 v45, v45
	v_exp_f32_e32 v46, v46
	v_exp_f32_e32 v47, v47
	v_exp_f32_e32 v48, v48
	v_exp_f32_e32 v49, v49
	v_add_f32_e32 v214, v34, v38
	v_add_f32_e32 v215, v35, v39
	v_add_f32_e32 v216, v36, v40
	v_add_f32_e32 v217, v37, v41
	v_add_f32_e32 v214, v214, v42
	v_add_f32_e32 v215, v215, v43
	v_add_f32_e32 v216, v216, v44
	v_add_f32_e32 v217, v217, v45
	v_add_f32_e32 v214, v214, v46
	v_add_f32_e32 v215, v215, v47
	v_add_f32_e32 v216, v216, v48
	v_add_f32_e32 v217, v217, v49
	s_waitcnt vmcnt(3)
	s_barrier
	ds_read_b128 v[182:185], v140 offset:16384
	ds_read_b128 v[186:189], v140 offset:24576
	ds_read_b128 v[190:193], v141 offset:16384
	ds_read_b128 v[194:197], v141 offset:24576
	s_mov_b32 s8, 0
.Lat_loop:
	ds_read_b128 v[198:201], v142 offset:16384
	ds_read_b128 v[202:205], v142 offset:24576
	ds_read_b128 v[206:209], v143 offset:16384
	ds_read_b128 v[210:213], v143 offset:24576
	s_add_i32 m0, s6, 0
	s_mov_b64 exec, s[20:21]
	global_load_lds_dwordx4 v146, s[14:15]
	s_add_i32 m0, s6, 1024
	s_mov_b64 exec, s[22:23]
	global_load_lds_dwordx4 v147, s[14:15]
	s_add_i32 m0, s7, 32768
	s_mov_b64 exec, -1
	global_load_lds_dwordx4 v149, s[14:15]
	v_add_u32_e32 v146, v146, v148
	v_add_u32_e32 v147, v147, v148
	v_add_u32_e32 v149, 0x38000, v149
	s_waitcnt lgkmcnt(7)
	v_mfma_f32_32x32x16_bf16 v[66:81], v[182:185], v[114:117], v[98:113]
	ds_read_b128 v[182:185], v144 offset:16384
	v_exp_f32_e32 v50, v50
	v_exp_f32_e32 v51, v51
	v_exp_f32_e32 v52, v52
	v_exp_f32_e32 v53, v53
	v_exp_f32_e32 v54, v54
	s_waitcnt lgkmcnt(7)
	v_mfma_f32_32x32x16_bf16 v[82:97], v[186:189], v[114:117], v[98:113]
	ds_read_b128 v[186:189], v144 offset:24576
	v_exp_f32_e32 v55, v55
	v_exp_f32_e32 v56, v56
	v_exp_f32_e32 v57, v57
	v_exp_f32_e32 v58, v58
	v_exp_f32_e32 v59, v59
	s_waitcnt lgkmcnt(7)
	v_mfma_f32_32x32x16_bf16 v[66:81], v[190:193], v[118:121], v[66:81]
	ds_read_b128 v[190:193], v145 offset:16384
	v_exp_f32_e32 v60, v60
	v_exp_f32_e32 v61, v61
	v_exp_f32_e32 v62, v62
	v_exp_f32_e32 v63, v63
	v_exp_f32_e32 v64, v64
	s_waitcnt lgkmcnt(7)
	v_mfma_f32_32x32x16_bf16 v[82:97], v[194:197], v[118:121], v[82:97]
	ds_read_b128 v[194:197], v145 offset:24576
	v_exp_f32_e32 v65, v65
	v_cvt_pk_bf16_f32 v158, v34, v35
	v_cvt_pk_bf16_f32 v159, v36, v37
	v_cvt_pk_bf16_f32 v160, v38, v39
	v_cvt_pk_bf16_f32 v161, v40, v41
	s_waitcnt lgkmcnt(7)
	v_mfma_f32_32x32x16_bf16 v[66:81], v[198:201], v[122:125], v[66:81]
	ds_read_b64_tr_b16 v[198:199], v150 offset:8192
	ds_read_b64_tr_b16 v[200:201], v150 offset:10240
	v_cvt_pk_bf16_f32 v162, v42, v43
	v_cvt_pk_bf16_f32 v163, v44, v45
	v_cvt_pk_bf16_f32 v164, v46, v47
	v_cvt_pk_bf16_f32 v165, v48, v49
	v_permlane32_swap_b32_e32 v158, v160
	s_waitcnt lgkmcnt(8)
	v_mfma_f32_32x32x16_bf16 v[82:97], v[202:205], v[122:125], v[82:97]
	ds_read_b64_tr_b16 v[202:203], v150 offset:8704
	ds_read_b64_tr_b16 v[204:205], v150 offset:10752
	v_permlane32_swap_b32_e32 v159, v161
	v_permlane32_swap_b32_e32 v162, v164
	v_permlane32_swap_b32_e32 v163, v165
	v_add_f32_e32 v214, v214, v50
	v_add_f32_e32 v215, v215, v51
	s_waitcnt lgkmcnt(9)
	v_mfma_f32_32x32x16_bf16 v[66:81], v[206:209], v[126:129], v[66:81]
	ds_read_b64_tr_b16 v[206:207], v150 offset:12288
	ds_read_b64_tr_b16 v[208:209], v150 offset:14336
	v_add_f32_e32 v216, v216, v52
	v_add_f32_e32 v217, v217, v53
	v_add_f32_e32 v214, v214, v54
	v_add_f32_e32 v215, v215, v55
	v_add_f32_e32 v216, v216, v56
	s_waitcnt lgkmcnt(10)
; __device__ __forceinline__ void finishSM(f32x16& p0, f32x16& p1, float alpha, float& l_reg, bf16x8& pa0, bf16x8& pa1, bf16x8& pa2, bf16x8& pa3) {
; #pragma unroll
;   for (int r = 0; r < 16; ++r) p1[r] = __builtin_amdgcn_exp2f(p1[r]);
;   float ps = 0;
; #pragma unroll
;   for (int r = 0; r < 16; ++r) ps += p0[r];
; #pragma unroll
;   for (int r = 0; r < 16; ++r) ps += p1[r];
;   { auto rr = __builtin_amdgcn_permlane32_swap(__float_as_uint(ps), __float_as_uint(ps), false, false);
;     ps = __uint_as_float(rr[0]) + __uint_as_float(rr[1]); }
;   l_reg = l_reg * alpha + ps;
;     ...
;   PK4(p0, 0, pa0); PK4(p0, 8, pa1); PK4(p1, 0, pa2); PK4(p1, 8, pa3);
;     ...
; }
; __device__ __forceinline__ void qkt(f32x16& p0, f32x16& p1, const bf16_t* Ks, const bf16x8* qr, const f32x16& negm, int r32, int hi) {
;   p0 = negm; p1 = negm;
; #pragma unroll
;   for (int d0 = 0; d0 < 6; ++d0) { int cb = (d0 * 16 + hi * 8) * 2;
;     bf16x8 b0 = *reinterpret_cast<const bf16x8*>((const char*)Ks + KSWZ(r32, cb));
;     bf16x8 b1 = *reinterpret_cast<const bf16x8*>((const char*)Ks + KSWZ(32 + r32, cb));
;     p0 = __builtin_amdgcn_mfma_f32_32x32x16_bf16(b0, qr[d0], p0, 0, 0, 0);
;     p1 = __builtin_amdgcn_mfma_f32_32x32x16_bf16(b1, qr[d0], p1, 0, 0, 0); }
; }
; __device__ __forceinline__ int v_st(int k, int c) { const int kk = (k & ~0xC) | ((k & 4) << 1) | ((k & 8) >> 1); return ((kk >> 3) * 4 + (c >> 5)) * 512 + ((kk & 7) * 32 + (c & 31)) * 2; }
; __device__ __forceinline__ int v_rd_base(int lane) { return ((lane & 3) << 3) | (((lane >> 2) & 3) << 6) | (((lane >> 4) & 1) << 5) | (((lane >> 5) & 1) << 8); }
; template <int OFF> __device__ __forceinline__ s16x4 tr_read(int vb) {
;   s16x4 r; asm volatile("ds_read_b64_tr_b16 %0, %1 offset:%2" : "=&v"(r) : "v"(vb), "i"(OFF) : "memory"); return r;
; }
; template <int D0> __device__ __forceinline__ void pv_one(f32x16& od, int vb, bf16x8 pa0, bf16x8 pa1, bf16x8 pa2, bf16x8 pa3) {
;   const s16x4 l0 = tr_read<v_rd_off(D0, 0, 0)>(vb), h0 = tr_read<v_rd_off(D0, 0, 1)>(vb), l1 = tr_read<v_rd_off(D0, 1, 0)>(vb), h1 = tr_read<v_rd_off(D0, 1, 1)>(vb);
;   const s16x4 l2 = tr_read<v_rd_off(D0, 2, 0)>(vb), h2 = tr_read<v_rd_off(D0, 2, 1)>(vb), l3 = tr_read<v_rd_off(D0, 3, 0)>(vb), h3 = tr_read<v_rd_off(D0, 3, 1)>(vb);
;   asm volatile("s_waitcnt lgkmcnt(0)" ::: "memory"); SBAR();
;     ...
;   od = __builtin_amdgcn_mfma_f32_32x32x16_bf16(pa0, PK(l0, h0), od, 0, 0, 0);
	v_mfma_f32_32x32x16_bf16 v[82:97], v[210:213], v[126:129], v[82:97]
	ds_read_b64_tr_b16 v[210:211], v150 offset:12800
	ds_read_b64_tr_b16 v[212:213], v150 offset:14848
	v_add_f32_e32 v217, v217, v57
	v_add_f32_e32 v214, v214, v58
	v_add_f32_e32 v215, v215, v59
	v_add_f32_e32 v216, v216, v60
	v_add_f32_e32 v217, v217, v61
	s_waitcnt lgkmcnt(11)
	v_mfma_f32_32x32x16_bf16 v[66:81], v[182:185], v[130:133], v[66:81]
	ds_read_b64_tr_b16 v[182:183], v150 offset:0
	ds_read_b64_tr_b16 v[184:185], v150 offset:2048
	v_add_f32_e32 v214, v214, v62
	v_add_f32_e32 v215, v215, v63
	v_add_f32_e32 v216, v216, v64
	v_add_f32_e32 v217, v217, v65
	v_add_f32_e32 v214, v214, v215
	s_waitcnt lgkmcnt(12)
	v_mfma_f32_32x32x16_bf16 v[82:97], v[186:189], v[130:133], v[82:97]
	ds_read_b64_tr_b16 v[186:187], v150 offset:512
	ds_read_b64_tr_b16 v[188:189], v150 offset:2560
	v_add_f32_e32 v216, v216, v217
	v_add_f32_e32 v214, v214, v216
	v_add_f32_e32 v174, v174, v214
	v_cvt_pk_bf16_f32 v166, v50, v51
	v_cvt_pk_bf16_f32 v167, v52, v53
	s_waitcnt lgkmcnt(13)
	v_mfma_f32_32x32x16_bf16 v[66:81], v[190:193], v[134:137], v[66:81]
	ds_read_b64_tr_b16 v[190:191], v150 offset:4096
	ds_read_b64_tr_b16 v[192:193], v150 offset:6144
	v_cvt_pk_bf16_f32 v168, v54, v55
	v_cvt_pk_bf16_f32 v169, v56, v57
	v_cvt_pk_bf16_f32 v170, v58, v59
	v_cvt_pk_bf16_f32 v171, v60, v61
	v_cvt_pk_bf16_f32 v172, v62, v63
	s_waitcnt lgkmcnt(14)
	v_mfma_f32_32x32x16_bf16 v[82:97], v[194:197], v[134:137], v[82:97]
	ds_read_b64_tr_b16 v[194:195], v150 offset:4608
	ds_read_b64_tr_b16 v[196:197], v150 offset:6656
	v_cvt_pk_bf16_f32 v173, v64, v65
	v_permlane32_swap_b32_e32 v166, v168
	v_permlane32_swap_b32_e32 v167, v169
	v_permlane32_swap_b32_e32 v170, v172
	v_permlane32_swap_b32_e32 v171, v173
	s_waitcnt lgkmcnt(6)
	v_mfma_f32_32x32x16_bf16 v[2:17], v[158:161], v[182:185], v[2:17]
	ds_read_b128 v[182:185], v140 offset:32768
	v_max3_f32 v177, v66, v67, v68
	v_max3_f32 v178, v69, v70, v71
	v_max3_f32 v177, v177, v72, v73
	s_waitcnt lgkmcnt(5)
	v_mfma_f32_32x32x16_bf16 v[18:33], v[158:161], v[186:189], v[18:33]
	ds_read_b128 v[186:189], v140 offset:40960
	v_max3_f32 v178, v178, v74, v75
	v_max3_f32 v177, v177, v76, v77
	v_max3_f32 v178, v178, v78, v79
	v_max3_f32 v177, v177, v80, v81
	v_max3_f32 v178, v178, v82, v83
	v_max3_f32 v177, v177, v84, v85
	s_waitcnt lgkmcnt(4)
	v_mfma_f32_32x32x16_bf16 v[2:17], v[162:165], v[190:193], v[2:17]
	ds_read_b128 v[190:193], v141 offset:32768
	v_max3_f32 v178, v178, v86, v87
	v_max3_f32 v177, v177, v88, v89
	v_max3_f32 v178, v178, v90, v91
	v_max3_f32 v177, v177, v92, v93
	v_max3_f32 v178, v178, v94, v95
	v_max3_f32 v177, v177, v96, v97
	s_waitcnt lgkmcnt(3)
	v_mfma_f32_32x32x16_bf16 v[18:33], v[162:165], v[194:197], v[18:33]
	ds_read_b128 v[194:197], v141 offset:40960
	v_max_f32_e32 v177, v177, v178
	v_mov_b32_e32 v178, v177
	s_nop 1
	v_permlane32_swap_b32_e32 v177, v178
	v_max_f32_e32 v177, v177, v178
	v_cmp_ge_f32_e32 vcc, 0x4138aa3b, v177
	s_cmp_eq_u64 vcc, exec
	s_cbranch_scc0 .Lat_rare1_2
.Lat_ri_1:
	v_mfma_f32_32x32x16_bf16 v[2:17], v[166:169], v[198:201], v[2:17]
	v_exp_f32_e32 v66, v66
	v_exp_f32_e32 v67, v67
	v_exp_f32_e32 v68, v68
	v_exp_f32_e32 v69, v69
	v_exp_f32_e32 v70, v70
	v_exp_f32_e32 v71, v71
	v_exp_f32_e32 v72, v72
	v_mfma_f32_32x32x16_bf16 v[18:33], v[166:169], v[202:205], v[18:33]
	v_exp_f32_e32 v73, v73
	v_exp_f32_e32 v74, v74
	v_exp_f32_e32 v75, v75
	v_exp_f32_e32 v76, v76
	v_exp_f32_e32 v77, v77
	v_exp_f32_e32 v78, v78
	v_exp_f32_e32 v79, v79
	v_mfma_f32_32x32x16_bf16 v[2:17], v[170:173], v[206:209], v[2:17]
	v_exp_f32_e32 v80, v80
	v_exp_f32_e32 v81, v81
	v_add_f32_e32 v214, v66, v70
	v_add_f32_e32 v215, v67, v71
	v_add_f32_e32 v216, v68, v72
	v_add_f32_e32 v217, v69, v73
	v_add_f32_e32 v214, v214, v74
	v_mfma_f32_32x32x16_bf16 v[18:33], v[170:173], v[210:213], v[18:33]
	v_add_f32_e32 v215, v215, v75
	v_add_f32_e32 v216, v216, v76
	v_add_f32_e32 v217, v217, v77
	v_add_f32_e32 v214, v214, v78
	v_add_f32_e32 v215, v215, v79
	v_add_f32_e32 v216, v216, v80
	v_add_f32_e32 v217, v217, v81
	s_waitcnt vmcnt(3)
	s_cmp_lg_u32 s9, 0
	s_cbranch_scc1 .Lat_rare2_3
.Lat_rr_4:
	s_waitcnt lgkmcnt(0)
	s_barrier
	ds_read_b128 v[198:201], v142 offset:32768
	ds_read_b128 v[202:205], v142 offset:40960
	ds_read_b128 v[206:209], v143 offset:32768
	ds_read_b128 v[210:213], v143 offset:40960
	s_add_i32 m0, s6, 16384
	s_mov_b64 exec, s[20:21]
	global_load_lds_dwordx4 v146, s[14:15]
	s_add_i32 m0, s6, 17408
	s_mov_b64 exec, s[22:23]
	global_load_lds_dwordx4 v147, s[14:15]
	s_add_i32 m0, s7, 49152
	s_mov_b64 exec, -1
	global_load_lds_dwordx4 v149, s[14:15]
	v_add_u32_e32 v146, v146, v148
	v_add_u32_e32 v147, v147, v148
	v_add_u32_e32 v149, 0x38000, v149
	v_mfma_f32_32x32x16_bf16 v[34:49], v[182:185], v[114:117], v[98:113]
	ds_read_b128 v[182:185], v144 offset:32768
	v_exp_f32_e32 v82, v82
	v_exp_f32_e32 v83, v83
	v_exp_f32_e32 v84, v84
	v_exp_f32_e32 v85, v85
	v_exp_f32_e32 v86, v86
	v_mfma_f32_32x32x16_bf16 v[50:65], v[186:189], v[114:117], v[98:113]
	ds_read_b128 v[186:189], v144 offset:40960
	v_exp_f32_e32 v87, v87
	v_exp_f32_e32 v88, v88
	v_exp_f32_e32 v89, v89
	v_exp_f32_e32 v90, v90
	v_exp_f32_e32 v91, v91
	v_mfma_f32_32x32x16_bf16 v[34:49], v[190:193], v[118:121], v[34:49]
	ds_read_b128 v[190:193], v145 offset:32768
	v_exp_f32_e32 v92, v92
	v_exp_f32_e32 v93, v93
	v_exp_f32_e32 v94, v94
	v_exp_f32_e32 v95, v95
	v_exp_f32_e32 v96, v96
	v_mfma_f32_32x32x16_bf16 v[50:65], v[194:197], v[118:121], v[50:65]
	ds_read_b128 v[194:197], v145 offset:40960
	v_exp_f32_e32 v97, v97
	v_cvt_pk_bf16_f32 v158, v66, v67
	v_cvt_pk_bf16_f32 v159, v68, v69
	v_cvt_pk_bf16_f32 v160, v70, v71
	v_cvt_pk_bf16_f32 v161, v72, v73
	s_waitcnt lgkmcnt(7)
; __device__ __forceinline__ void finishSM(f32x16& p0, f32x16& p1, float alpha, float& l_reg, bf16x8& pa0, bf16x8& pa1, bf16x8& pa2, bf16x8& pa3) {
; #pragma unroll
;   for (int r = 0; r < 16; ++r) p1[r] = __builtin_amdgcn_exp2f(p1[r]);
;   float ps = 0;
; #pragma unroll
;   for (int r = 0; r < 16; ++r) ps += p0[r];
; #pragma unroll
;   for (int r = 0; r < 16; ++r) ps += p1[r];
;   { auto rr = __builtin_amdgcn_permlane32_swap(__float_as_uint(ps), __float_as_uint(ps), false, false);
;     ps = __uint_as_float(rr[0]) + __uint_as_float(rr[1]); }
;   l_reg = l_reg * alpha + ps;
;     ...
;   PK4(p0, 0, pa0); PK4(p0, 8, pa1); PK4(p1, 0, pa2); PK4(p1, 8, pa3);
;     ...
; }
; __device__ __forceinline__ void qkt(f32x16& p0, f32x16& p1, const bf16_t* Ks, const bf16x8* qr, const f32x16& negm, int r32, int hi) {
;   p0 = negm; p1 = negm;
; #pragma unroll
;   for (int d0 = 0; d0 < 6; ++d0) { int cb = (d0 * 16 + hi * 8) * 2;
;     bf16x8 b0 = *reinterpret_cast<const bf16x8*>((const char*)Ks + KSWZ(r32, cb));
;     bf16x8 b1 = *reinterpret_cast<const bf16x8*>((const char*)Ks + KSWZ(32 + r32, cb));
;     p0 = __builtin_amdgcn_mfma_f32_32x32x16_bf16(b0, qr[d0], p0, 0, 0, 0);
;     p1 = __builtin_amdgcn_mfma_f32_32x32x16_bf16(b1, qr[d0], p1, 0, 0, 0); }
; }
; __device__ __forceinline__ int v_st(int k, int c) { const int kk = (k & ~0xC) | ((k & 4) << 1) | ((k & 8) >> 1); return ((kk >> 3) * 4 + (c >> 5)) * 512 + ((kk & 7) * 32 + (c & 31)) * 2; }
; __device__ __forceinline__ int v_rd_base(int lane) { return ((lane & 3) << 3) | (((lane >> 2) & 3) << 6) | (((lane >> 4) & 1) << 5) | (((lane >> 5) & 1) << 8); }
; template <int OFF> __device__ __forceinline__ s16x4 tr_read(int vb) {
;   s16x4 r; asm volatile("ds_read_b64_tr_b16 %0, %1 offset:%2" : "=&v"(r) : "v"(vb), "i"(OFF) : "memory"); return r;
; }
; template <int D0> __device__ __forceinline__ void pv_one(f32x16& od, int vb, bf16x8 pa0, bf16x8 pa1, bf16x8 pa2, bf16x8 pa3) {
;   const s16x4 l0 = tr_read<v_rd_off(D0, 0, 0)>(vb), h0 = tr_read<v_rd_off(D0, 0, 1)>(vb), l1 = tr_read<v_rd_off(D0, 1, 0)>(vb), h1 = tr_read<v_rd_off(D0, 1, 1)>(vb);
;   const s16x4 l2 = tr_read<v_rd_off(D0, 2, 0)>(vb), h2 = tr_read<v_rd_off(D0, 2, 1)>(vb), l3 = tr_read<v_rd_off(D0, 3, 0)>(vb), h3 = tr_read<v_rd_off(D0, 3, 1)>(vb);
;   asm volatile("s_waitcnt lgkmcnt(0)" ::: "memory"); SBAR();
;     ...
;   od = __builtin_amdgcn_mfma_f32_32x32x16_bf16(pa0, PK(l0, h0), od, 0, 0, 0);
	v_mfma_f32_32x32x16_bf16 v[34:49], v[198:201], v[122:125], v[34:49]
	ds_read_b64_tr_b16 v[198:199], v150 offset:24576
	ds_read_b64_tr_b16 v[200:201], v150 offset:26624
	v_cvt_pk_bf16_f32 v162, v74, v75
	v_cvt_pk_bf16_f32 v163, v76, v77
	v_cvt_pk_bf16_f32 v164, v78, v79
	v_cvt_pk_bf16_f32 v165, v80, v81
	v_permlane32_swap_b32_e32 v158, v160
	s_waitcnt lgkmcnt(8)
	v_mfma_f32_32x32x16_bf16 v[50:65], v[202:205], v[122:125], v[50:65]
	ds_read_b64_tr_b16 v[202:203], v150 offset:25088
	ds_read_b64_tr_b16 v[204:205], v150 offset:27136
	v_permlane32_swap_b32_e32 v159, v161
	v_permlane32_swap_b32_e32 v162, v164
	v_permlane32_swap_b32_e32 v163, v165
	v_add_f32_e32 v214, v214, v82
	v_add_f32_e32 v215, v215, v83
	s_waitcnt lgkmcnt(9)
	v_mfma_f32_32x32x16_bf16 v[34:49], v[206:209], v[126:129], v[34:49]
	ds_read_b64_tr_b16 v[206:207], v150 offset:28672
	ds_read_b64_tr_b16 v[208:209], v150 offset:30720
	v_add_f32_e32 v216, v216, v84
	v_add_f32_e32 v217, v217, v85
	v_add_f32_e32 v214, v214, v86
	v_add_f32_e32 v215, v215, v87
	v_add_f32_e32 v216, v216, v88
	s_waitcnt lgkmcnt(10)
	v_mfma_f32_32x32x16_bf16 v[50:65], v[210:213], v[126:129], v[50:65]
	ds_read_b64_tr_b16 v[210:211], v150 offset:29184
	ds_read_b64_tr_b16 v[212:213], v150 offset:31232
	v_add_f32_e32 v217, v217, v89
	v_add_f32_e32 v214, v214, v90
	v_add_f32_e32 v215, v215, v91
	v_add_f32_e32 v216, v216, v92
	v_add_f32_e32 v217, v217, v93
	s_waitcnt lgkmcnt(11)
	v_mfma_f32_32x32x16_bf16 v[34:49], v[182:185], v[130:133], v[34:49]
	ds_read_b64_tr_b16 v[182:183], v150 offset:16384
	ds_read_b64_tr_b16 v[184:185], v150 offset:18432
	v_add_f32_e32 v214, v214, v94
	v_add_f32_e32 v215, v215, v95
	v_add_f32_e32 v216, v216, v96
	v_add_f32_e32 v217, v217, v97
	v_add_f32_e32 v214, v214, v215
	s_waitcnt lgkmcnt(12)
	v_mfma_f32_32x32x16_bf16 v[50:65], v[186:189], v[130:133], v[50:65]
	ds_read_b64_tr_b16 v[186:187], v150 offset:16896
	ds_read_b64_tr_b16 v[188:189], v150 offset:18944
	v_add_f32_e32 v216, v216, v217
	v_add_f32_e32 v214, v214, v216
	v_add_f32_e32 v174, v174, v214
	v_cvt_pk_bf16_f32 v166, v82, v83
	v_cvt_pk_bf16_f32 v167, v84, v85
	s_waitcnt lgkmcnt(13)
	v_mfma_f32_32x32x16_bf16 v[34:49], v[190:193], v[134:137], v[34:49]
	ds_read_b64_tr_b16 v[190:191], v150 offset:20480
	ds_read_b64_tr_b16 v[192:193], v150 offset:22528
	v_cvt_pk_bf16_f32 v168, v86, v87
	v_cvt_pk_bf16_f32 v169, v88, v89
	v_cvt_pk_bf16_f32 v170, v90, v91
	v_cvt_pk_bf16_f32 v171, v92, v93
	v_cvt_pk_bf16_f32 v172, v94, v95
	s_waitcnt lgkmcnt(14)
	v_mfma_f32_32x32x16_bf16 v[50:65], v[194:197], v[134:137], v[50:65]
	ds_read_b64_tr_b16 v[194:195], v150 offset:20992
	ds_read_b64_tr_b16 v[196:197], v150 offset:23040
	v_cvt_pk_bf16_f32 v173, v96, v97
	v_permlane32_swap_b32_e32 v166, v168
	v_permlane32_swap_b32_e32 v167, v169
	v_permlane32_swap_b32_e32 v170, v172
	v_permlane32_swap_b32_e32 v171, v173
	s_waitcnt lgkmcnt(6)
	v_mfma_f32_32x32x16_bf16 v[2:17], v[158:161], v[182:185], v[2:17]
	ds_read_b128 v[182:185], v140 offset:49152
	v_max3_f32 v177, v34, v35, v36
	v_max3_f32 v178, v37, v38, v39
	v_max3_f32 v177, v177, v40, v41
	s_waitcnt lgkmcnt(5)
	v_mfma_f32_32x32x16_bf16 v[18:33], v[158:161], v[186:189], v[18:33]
	ds_read_b128 v[186:189], v140 offset:57344
	v_max3_f32 v178, v178, v42, v43
	v_max3_f32 v177, v177, v44, v45
	v_max3_f32 v178, v178, v46, v47
	v_max3_f32 v177, v177, v48, v49
	v_max3_f32 v178, v178, v50, v51
	v_max3_f32 v177, v177, v52, v53
	s_waitcnt lgkmcnt(4)
	v_mfma_f32_32x32x16_bf16 v[2:17], v[162:165], v[190:193], v[2:17]
	ds_read_b128 v[190:193], v141 offset:49152
	v_max3_f32 v178, v178, v54, v55
	v_max3_f32 v177, v177, v56, v57
	v_max3_f32 v178, v178, v58, v59
	v_max3_f32 v177, v177, v60, v61
	v_max3_f32 v178, v178, v62, v63
	v_max3_f32 v177, v177, v64, v65
	s_waitcnt lgkmcnt(3)
	v_mfma_f32_32x32x16_bf16 v[18:33], v[162:165], v[194:197], v[18:33]
	ds_read_b128 v[194:197], v141 offset:57344
	v_max_f32_e32 v177, v177, v178
	v_mov_b32_e32 v178, v177
	s_nop 1
	v_permlane32_swap_b32_e32 v177, v178
	v_max_f32_e32 v177, v177, v178
	v_cmp_ge_f32_e32 vcc, 0x4138aa3b, v177
	s_cmp_eq_u64 vcc, exec
	s_cbranch_scc0 .Lat_rare1_6
.Lat_ri_5:
	v_mfma_f32_32x32x16_bf16 v[2:17], v[166:169], v[198:201], v[2:17]
	v_exp_f32_e32 v34, v34
	v_exp_f32_e32 v35, v35
	v_exp_f32_e32 v36, v36
	v_exp_f32_e32 v37, v37
	v_exp_f32_e32 v38, v38
	v_exp_f32_e32 v39, v39
	v_exp_f32_e32 v40, v40
	v_mfma_f32_32x32x16_bf16 v[18:33], v[166:169], v[202:205], v[18:33]
	v_exp_f32_e32 v41, v41
	v_exp_f32_e32 v42, v42
	v_exp_f32_e32 v43, v43
	v_exp_f32_e32 v44, v44
	v_exp_f32_e32 v45, v45
	v_exp_f32_e32 v46, v46
	v_exp_f32_e32 v47, v47
	v_mfma_f32_32x32x16_bf16 v[2:17], v[170:173], v[206:209], v[2:17]
	v_exp_f32_e32 v48, v48
	v_exp_f32_e32 v49, v49
	v_add_f32_e32 v214, v34, v38
	v_add_f32_e32 v215, v35, v39
	v_add_f32_e32 v216, v36, v40
	v_add_f32_e32 v217, v37, v41
	v_add_f32_e32 v214, v214, v42
	v_mfma_f32_32x32x16_bf16 v[18:33], v[170:173], v[210:213], v[18:33]
	v_add_f32_e32 v215, v215, v43
	v_add_f32_e32 v216, v216, v44
	v_add_f32_e32 v217, v217, v45
	v_add_f32_e32 v214, v214, v46
	v_add_f32_e32 v215, v215, v47
	v_add_f32_e32 v216, v216, v48
	v_add_f32_e32 v217, v217, v49
	s_waitcnt vmcnt(3)
	s_cmp_lg_u32 s9, 0
	s_cbranch_scc1 .Lat_rare2_7
; __device__ __forceinline__ void finishSM(f32x16& p0, f32x16& p1, float alpha, float& l_reg, bf16x8& pa0, bf16x8& pa1, bf16x8& pa2, bf16x8& pa3) {
; #pragma unroll
;   for (int r = 0; r < 16; ++r) p1[r] = __builtin_amdgcn_exp2f(p1[r]);
;   float ps = 0;
; #pragma unroll
;   for (int r = 0; r < 16; ++r) ps += p0[r];
; #pragma unroll
;   for (int r = 0; r < 16; ++r) ps += p1[r];
;   { auto rr = __builtin_amdgcn_permlane32_swap(__float_as_uint(ps), __float_as_uint(ps), false, false);
;     ps = __uint_as_float(rr[0]) + __uint_as_float(rr[1]); }
;   l_reg = l_reg * alpha + ps;
;     ...
;   PK4(p0, 0, pa0); PK4(p0, 8, pa1); PK4(p1, 0, pa2); PK4(p1, 8, pa3);
;     ...
; }
; __device__ __forceinline__ void qkt(f32x16& p0, f32x16& p1, const bf16_t* Ks, const bf16x8* qr, const f32x16& negm, int r32, int hi) {
;   p0 = negm; p1 = negm;
; #pragma unroll
;   for (int d0 = 0; d0 < 6; ++d0) { int cb = (d0 * 16 + hi * 8) * 2;
;     bf16x8 b0 = *reinterpret_cast<const bf16x8*>((const char*)Ks + KSWZ(r32, cb));
;     bf16x8 b1 = *reinterpret_cast<const bf16x8*>((const char*)Ks + KSWZ(32 + r32, cb));
;     p0 = __builtin_amdgcn_mfma_f32_32x32x16_bf16(b0, qr[d0], p0, 0, 0, 0);
;     p1 = __builtin_amdgcn_mfma_f32_32x32x16_bf16(b1, qr[d0], p1, 0, 0, 0); }
; }
; __device__ __forceinline__ int v_st(int k, int c) { const int kk = (k & ~0xC) | ((k & 4) << 1) | ((k & 8) >> 1); return ((kk >> 3) * 4 + (c >> 5)) * 512 + ((kk & 7) * 32 + (c & 31)) * 2; }
; __device__ __forceinline__ int v_rd_base(int lane) { return ((lane & 3) << 3) | (((lane >> 2) & 3) << 6) | (((lane >> 4) & 1) << 5) | (((lane >> 5) & 1) << 8); }
; template <int OFF> __device__ __forceinline__ s16x4 tr_read(int vb) {
;   s16x4 r; asm volatile("ds_read_b64_tr_b16 %0, %1 offset:%2" : "=&v"(r) : "v"(vb), "i"(OFF) : "memory"); return r;
; }
; template <int D0> __device__ __forceinline__ void pv_one(f32x16& od, int vb, bf16x8 pa0, bf16x8 pa1, bf16x8 pa2, bf16x8 pa3) {
;   const s16x4 l0 = tr_read<v_rd_off(D0, 0, 0)>(vb), h0 = tr_read<v_rd_off(D0, 0, 1)>(vb), l1 = tr_read<v_rd_off(D0, 1, 0)>(vb), h1 = tr_read<v_rd_off(D0, 1, 1)>(vb);
;   const s16x4 l2 = tr_read<v_rd_off(D0, 2, 0)>(vb), h2 = tr_read<v_rd_off(D0, 2, 1)>(vb), l3 = tr_read<v_rd_off(D0, 3, 0)>(vb), h3 = tr_read<v_rd_off(D0, 3, 1)>(vb);
;   asm volatile("s_waitcnt lgkmcnt(0)" ::: "memory"); SBAR();
;     ...
;   od = __builtin_amdgcn_mfma_f32_32x32x16_bf16(pa0, PK(l0, h0), od, 0, 0, 0);
.Lat_rr_8:
	s_waitcnt lgkmcnt(0)
	s_barrier
	ds_read_b128 v[198:201], v142 offset:49152
	ds_read_b128 v[202:205], v142 offset:57344
	ds_read_b128 v[206:209], v143 offset:49152
	ds_read_b128 v[210:213], v143 offset:57344
	s_add_i32 m0, s6, 32768
	s_mov_b64 exec, s[20:21]
	global_load_lds_dwordx4 v146, s[14:15]
	s_add_i32 m0, s6, 33792
	s_mov_b64 exec, s[22:23]
	global_load_lds_dwordx4 v147, s[14:15]
	s_add_i32 m0, s7, 0
	s_mov_b64 exec, -1
	global_load_lds_dwordx4 v149, s[14:15]
	v_add_u32_e32 v146, v146, v148
	v_add_u32_e32 v147, v147, v148
	v_add_u32_e32 v149, 0x38000, v149
	v_mfma_f32_32x32x16_bf16 v[66:81], v[182:185], v[114:117], v[98:113]
	ds_read_b128 v[182:185], v144 offset:49152
	v_exp_f32_e32 v50, v50
	v_exp_f32_e32 v51, v51
	v_exp_f32_e32 v52, v52
	v_exp_f32_e32 v53, v53
	v_exp_f32_e32 v54, v54
	v_mfma_f32_32x32x16_bf16 v[82:97], v[186:189], v[114:117], v[98:113]
	ds_read_b128 v[186:189], v144 offset:57344
	v_exp_f32_e32 v55, v55
	v_exp_f32_e32 v56, v56
	v_exp_f32_e32 v57, v57
	v_exp_f32_e32 v58, v58
	v_exp_f32_e32 v59, v59
	v_mfma_f32_32x32x16_bf16 v[66:81], v[190:193], v[118:121], v[66:81]
	ds_read_b128 v[190:193], v145 offset:49152
	v_exp_f32_e32 v60, v60
	v_exp_f32_e32 v61, v61
	v_exp_f32_e32 v62, v62
	v_exp_f32_e32 v63, v63
	v_exp_f32_e32 v64, v64
	v_mfma_f32_32x32x16_bf16 v[82:97], v[194:197], v[118:121], v[82:97]
	ds_read_b128 v[194:197], v145 offset:57344
	v_exp_f32_e32 v65, v65
	v_cvt_pk_bf16_f32 v158, v34, v35
	v_cvt_pk_bf16_f32 v159, v36, v37
	v_cvt_pk_bf16_f32 v160, v38, v39
	v_cvt_pk_bf16_f32 v161, v40, v41
	s_waitcnt lgkmcnt(7)
	v_mfma_f32_32x32x16_bf16 v[66:81], v[198:201], v[122:125], v[66:81]
	ds_read_b64_tr_b16 v[198:199], v150 offset:40960
	ds_read_b64_tr_b16 v[200:201], v150 offset:43008
	v_cvt_pk_bf16_f32 v162, v42, v43
	v_cvt_pk_bf16_f32 v163, v44, v45
	v_cvt_pk_bf16_f32 v164, v46, v47
	v_cvt_pk_bf16_f32 v165, v48, v49
	v_permlane32_swap_b32_e32 v158, v160
	s_waitcnt lgkmcnt(8)
	v_mfma_f32_32x32x16_bf16 v[82:97], v[202:205], v[122:125], v[82:97]
	ds_read_b64_tr_b16 v[202:203], v150 offset:41472
	ds_read_b64_tr_b16 v[204:205], v150 offset:43520
	v_permlane32_swap_b32_e32 v159, v161
	v_permlane32_swap_b32_e32 v162, v164
	v_permlane32_swap_b32_e32 v163, v165
	v_add_f32_e32 v214, v214, v50
	v_add_f32_e32 v215, v215, v51
	s_waitcnt lgkmcnt(9)
	v_mfma_f32_32x32x16_bf16 v[66:81], v[206:209], v[126:129], v[66:81]
	ds_read_b64_tr_b16 v[206:207], v150 offset:45056
	ds_read_b64_tr_b16 v[208:209], v150 offset:47104
	v_add_f32_e32 v216, v216, v52
	v_add_f32_e32 v217, v217, v53
	v_add_f32_e32 v214, v214, v54
	v_add_f32_e32 v215, v215, v55
	v_add_f32_e32 v216, v216, v56
	s_waitcnt lgkmcnt(10)
	v_mfma_f32_32x32x16_bf16 v[82:97], v[210:213], v[126:129], v[82:97]
	ds_read_b64_tr_b16 v[210:211], v150 offset:45568
	ds_read_b64_tr_b16 v[212:213], v150 offset:47616
	v_add_f32_e32 v217, v217, v57
	v_add_f32_e32 v214, v214, v58
	v_add_f32_e32 v215, v215, v59
	v_add_f32_e32 v216, v216, v60
	v_add_f32_e32 v217, v217, v61
	s_waitcnt lgkmcnt(11)
	v_mfma_f32_32x32x16_bf16 v[66:81], v[182:185], v[130:133], v[66:81]
	ds_read_b64_tr_b16 v[182:183], v150 offset:32768
	ds_read_b64_tr_b16 v[184:185], v150 offset:34816
	v_add_f32_e32 v214, v214, v62
	v_add_f32_e32 v215, v215, v63
	v_add_f32_e32 v216, v216, v64
	v_add_f32_e32 v217, v217, v65
	v_add_f32_e32 v214, v214, v215
	s_waitcnt lgkmcnt(12)
	v_mfma_f32_32x32x16_bf16 v[82:97], v[186:189], v[130:133], v[82:97]
	ds_read_b64_tr_b16 v[186:187], v150 offset:33280
	ds_read_b64_tr_b16 v[188:189], v150 offset:35328
	v_add_f32_e32 v216, v216, v217
	v_add_f32_e32 v214, v214, v216
	v_add_f32_e32 v174, v174, v214
	v_cvt_pk_bf16_f32 v166, v50, v51
	v_cvt_pk_bf16_f32 v167, v52, v53
	s_waitcnt lgkmcnt(13)
	v_mfma_f32_32x32x16_bf16 v[66:81], v[190:193], v[134:137], v[66:81]
	ds_read_b64_tr_b16 v[190:191], v150 offset:36864
	ds_read_b64_tr_b16 v[192:193], v150 offset:38912
	v_cvt_pk_bf16_f32 v168, v54, v55
	v_cvt_pk_bf16_f32 v169, v56, v57
	v_cvt_pk_bf16_f32 v170, v58, v59
	v_cvt_pk_bf16_f32 v171, v60, v61
	v_cvt_pk_bf16_f32 v172, v62, v63
	s_waitcnt lgkmcnt(14)
	v_mfma_f32_32x32x16_bf16 v[82:97], v[194:197], v[134:137], v[82:97]
	ds_read_b64_tr_b16 v[194:195], v150 offset:37376
	ds_read_b64_tr_b16 v[196:197], v150 offset:39424
	v_cvt_pk_bf16_f32 v173, v64, v65
	v_permlane32_swap_b32_e32 v166, v168
	v_permlane32_swap_b32_e32 v167, v169
	v_permlane32_swap_b32_e32 v170, v172
	v_permlane32_swap_b32_e32 v171, v173
	s_waitcnt lgkmcnt(6)
	v_mfma_f32_32x32x16_bf16 v[2:17], v[158:161], v[182:185], v[2:17]
	ds_read_b128 v[182:185], v140 offset:0
	v_max3_f32 v177, v66, v67, v68
	v_max3_f32 v178, v69, v70, v71
	v_max3_f32 v177, v177, v72, v73
	s_waitcnt lgkmcnt(5)
	v_mfma_f32_32x32x16_bf16 v[18:33], v[158:161], v[186:189], v[18:33]
	ds_read_b128 v[186:189], v140 offset:8192
	v_max3_f32 v178, v178, v74, v75
	v_max3_f32 v177, v177, v76, v77
	v_max3_f32 v178, v178, v78, v79
	v_max3_f32 v177, v177, v80, v81
	v_max3_f32 v178, v178, v82, v83
	v_max3_f32 v177, v177, v84, v85
	s_waitcnt lgkmcnt(4)
	v_mfma_f32_32x32x16_bf16 v[2:17], v[162:165], v[190:193], v[2:17]
	ds_read_b128 v[190:193], v141 offset:0
	v_max3_f32 v178, v178, v86, v87
	v_max3_f32 v177, v177, v88, v89
	v_max3_f32 v178, v178, v90, v91
	v_max3_f32 v177, v177, v92, v93
	v_max3_f32 v178, v178, v94, v95
	v_max3_f32 v177, v177, v96, v97
	s_waitcnt lgkmcnt(3)
	v_mfma_f32_32x32x16_bf16 v[18:33], v[162:165], v[194:197], v[18:33]
	ds_read_b128 v[194:197], v141 offset:8192
	v_max_f32_e32 v177, v177, v178
	v_mov_b32_e32 v178, v177
	s_nop 1
	v_permlane32_swap_b32_e32 v177, v178
	v_max_f32_e32 v177, v177, v178
	v_cmp_ge_f32_e32 vcc, 0x4138aa3b, v177
	s_cmp_eq_u64 vcc, exec
	s_cbranch_scc0 .Lat_rare1_10

; __device__ __forceinline__ void finishSM(f32x16& p0, f32x16& p1, float alpha, float& l_reg, bf16x8& pa0, bf16x8& pa1, bf16x8& pa2, bf16x8& pa3) {
; #pragma unroll
;   for (int r = 0; r < 16; ++r) p1[r] = __builtin_amdgcn_exp2f(p1[r]);
;   float ps = 0;
; #pragma unroll
;   for (int r = 0; r < 16; ++r) ps += p0[r];
; #pragma unroll
;   for (int r = 0; r < 16; ++r) ps += p1[r];
;   { auto rr = __builtin_amdgcn_permlane32_swap(__float_as_uint(ps), __float_as_uint(ps), false, false);
;     ps = __uint_as_float(rr[0]) + __uint_as_float(rr[1]); }
;   l_reg = l_reg * alpha + ps;
;     ...
;   PK4(p0, 0, pa0); PK4(p0, 8, pa1); PK4(p1, 0, pa2); PK4(p1, 8, pa3);
;     ...
; }
; __device__ __forceinline__ void qkt(f32x16& p0, f32x16& p1, const bf16_t* Ks, const bf16x8* qr, const f32x16& negm, int r32, int hi) {
;   p0 = negm; p1 = negm;
; #pragma unroll
;   for (int d0 = 0; d0 < 6; ++d0) { int cb = (d0 * 16 + hi * 8) * 2;
;     bf16x8 b0 = *reinterpret_cast<const bf16x8*>((const char*)Ks + KSWZ(r32, cb));
;     bf16x8 b1 = *reinterpret_cast<const bf16x8*>((const char*)Ks + KSWZ(32 + r32, cb));
;     p0 = __builtin_amdgcn_mfma_f32_32x32x16_bf16(b0, qr[d0], p0, 0, 0, 0);
;     p1 = __builtin_amdgcn_mfma_f32_32x32x16_bf16(b1, qr[d0], p1, 0, 0, 0); }
; }
; __device__ __forceinline__ int v_st(int k, int c) { const int kk = (k & ~0xC) | ((k & 4) << 1) | ((k & 8) >> 1); return ((kk >> 3) * 4 + (c >> 5)) * 512 + ((kk & 7) * 32 + (c & 31)) * 2; }
; __device__ __forceinline__ int v_rd_base(int lane) { return ((lane & 3) << 3) | (((lane >> 2) & 3) << 6) | (((lane >> 4) & 1) << 5) | (((lane >> 5) & 1) << 8); }
; template <int OFF> __device__ __forceinline__ s16x4 tr_read(int vb) {
;   s16x4 r; asm volatile("ds_read_b64_tr_b16 %0, %1 offset:%2" : "=&v"(r) : "v"(vb), "i"(OFF) : "memory"); return r;
; }
; template <int D0> __device__ __forceinline__ void pv_one(f32x16& od, int vb, bf16x8 pa0, bf16x8 pa1, bf16x8 pa2, bf16x8 pa3) {
;   const s16x4 l0 = tr_read<v_rd_off(D0, 0, 0)>(vb), h0 = tr_read<v_rd_off(D0, 0, 1)>(vb), l1 = tr_read<v_rd_off(D0, 1, 0)>(vb), h1 = tr_read<v_rd_off(D0, 1, 1)>(vb);
;   const s16x4 l2 = tr_read<v_rd_off(D0, 2, 0)>(vb), h2 = tr_read<v_rd_off(D0, 2, 1)>(vb), l3 = tr_read<v_rd_off(D0, 3, 0)>(vb), h3 = tr_read<v_rd_off(D0, 3, 1)>(vb);
;   asm volatile("s_waitcnt lgkmcnt(0)" ::: "memory"); SBAR();
;     ...
;   od = __builtin_amdgcn_mfma_f32_32x32x16_bf16(pa0, PK(l0, h0), od, 0, 0, 0);
.Lat_rr_12:
	s_waitcnt lgkmcnt(0)
	s_barrier
	ds_read_b128 v[198:201], v142 offset:0
	ds_read_b128 v[202:205], v142 offset:8192
	ds_read_b128 v[206:209], v143 offset:0
	ds_read_b128 v[210:213], v143 offset:8192
	s_add_i32 m0, s6, 49152
	s_mov_b64 exec, s[20:21]
	global_load_lds_dwordx4 v146, s[14:15]
	s_add_i32 m0, s6, 50176
	s_mov_b64 exec, s[22:23]
	global_load_lds_dwordx4 v147, s[14:15]
	s_add_i32 m0, s7, 16384
	s_mov_b64 exec, -1
	global_load_lds_dwordx4 v149, s[14:15]
	v_add_u32_e32 v146, v146, v148
	v_add_u32_e32 v147, v147, v148
	v_add_u32_e32 v149, 0x38000, v149
	v_mfma_f32_32x32x16_bf16 v[34:49], v[182:185], v[114:117], v[98:113]
	ds_read_b128 v[182:185], v144 offset:0
	v_exp_f32_e32 v82, v82
	v_exp_f32_e32 v83, v83
	v_exp_f32_e32 v84, v84
	v_exp_f32_e32 v85, v85
	v_exp_f32_e32 v86, v86
	v_mfma_f32_32x32x16_bf16 v[50:65], v[186:189], v[114:117], v[98:113]
	ds_read_b128 v[186:189], v144 offset:8192
	v_exp_f32_e32 v87, v87
	v_exp_f32_e32 v88, v88
	v_exp_f32_e32 v89, v89
	v_exp_f32_e32 v90, v90
	v_exp_f32_e32 v91, v91
	v_mfma_f32_32x32x16_bf16 v[34:49], v[190:193], v[118:121], v[34:49]
	ds_read_b128 v[190:193], v145 offset:0
	v_exp_f32_e32 v92, v92
	v_exp_f32_e32 v93, v93
	v_exp_f32_e32 v94, v94
	v_exp_f32_e32 v95, v95
	v_exp_f32_e32 v96, v96
	v_mfma_f32_32x32x16_bf16 v[50:65], v[194:197], v[118:121], v[50:65]
	ds_read_b128 v[194:197], v145 offset:8192
	v_exp_f32_e32 v97, v97
	v_cvt_pk_bf16_f32 v158, v66, v67
	v_cvt_pk_bf16_f32 v159, v68, v69
	v_cvt_pk_bf16_f32 v160, v70, v71
	v_cvt_pk_bf16_f32 v161, v72, v73
	s_waitcnt lgkmcnt(7)
	v_mfma_f32_32x32x16_bf16 v[34:49], v[198:201], v[122:125], v[34:49]
	ds_read_b64_tr_b16 v[198:199], v150 offset:57344
	ds_read_b64_tr_b16 v[200:201], v150 offset:59392
	v_cvt_pk_bf16_f32 v162, v74, v75
	v_cvt_pk_bf16_f32 v163, v76, v77
	v_cvt_pk_bf16_f32 v164, v78, v79
	v_cvt_pk_bf16_f32 v165, v80, v81
	v_permlane32_swap_b32_e32 v158, v160
	s_waitcnt lgkmcnt(8)
	v_mfma_f32_32x32x16_bf16 v[50:65], v[202:205], v[122:125], v[50:65]
	ds_read_b64_tr_b16 v[202:203], v150 offset:57856
	ds_read_b64_tr_b16 v[204:205], v150 offset:59904
	v_permlane32_swap_b32_e32 v159, v161
	v_permlane32_swap_b32_e32 v162, v164
	v_permlane32_swap_b32_e32 v163, v165
	v_add_f32_e32 v214, v214, v82
	v_add_f32_e32 v215, v215, v83
	s_waitcnt lgkmcnt(9)
	v_mfma_f32_32x32x16_bf16 v[34:49], v[206:209], v[126:129], v[34:49]
	ds_read_b64_tr_b16 v[206:207], v150 offset:61440
	ds_read_b64_tr_b16 v[208:209], v150 offset:63488
	v_add_f32_e32 v216, v216, v84
	v_add_f32_e32 v217, v217, v85
	v_add_f32_e32 v214, v214, v86
	v_add_f32_e32 v215, v215, v87
	v_add_f32_e32 v216, v216, v88
	s_waitcnt lgkmcnt(10)
	v_mfma_f32_32x32x16_bf16 v[50:65], v[210:213], v[126:129], v[50:65]
	ds_read_b64_tr_b16 v[210:211], v150 offset:61952
	ds_read_b64_tr_b16 v[212:213], v150 offset:64000
	v_add_f32_e32 v217, v217, v89
	v_add_f32_e32 v214, v214, v90
	v_add_f32_e32 v215, v215, v91
	v_add_f32_e32 v216, v216, v92
	v_add_f32_e32 v217, v217, v93
	s_waitcnt lgkmcnt(11)
	v_mfma_f32_32x32x16_bf16 v[34:49], v[182:185], v[130:133], v[34:49]
	ds_read_b64_tr_b16 v[182:183], v150 offset:49152
	ds_read_b64_tr_b16 v[184:185], v150 offset:51200
	v_add_f32_e32 v214, v214, v94
	v_add_f32_e32 v215, v215, v95
	v_add_f32_e32 v216, v216, v96
	v_add_f32_e32 v217, v217, v97
	v_add_f32_e32 v214, v214, v215
	s_waitcnt lgkmcnt(12)
	v_mfma_f32_32x32x16_bf16 v[50:65], v[186:189], v[130:133], v[50:65]
	ds_read_b64_tr_b16 v[186:187], v150 offset:49664
	ds_read_b64_tr_b16 v[188:189], v150 offset:51712
	v_add_f32_e32 v216, v216, v217
	v_add_f32_e32 v214, v214, v216
	v_add_f32_e32 v174, v174, v214
	v_cvt_pk_bf16_f32 v166, v82, v83
	v_cvt_pk_bf16_f32 v167, v84, v85
	s_waitcnt lgkmcnt(13)
	v_mfma_f32_32x32x16_bf16 v[34:49], v[190:193], v[134:137], v[34:49]
	ds_read_b64_tr_b16 v[190:191], v150 offset:53248
	ds_read_b64_tr_b16 v[192:193], v150 offset:55296
	v_cvt_pk_bf16_f32 v168, v86, v87
	v_cvt_pk_bf16_f32 v169, v88, v89
	v_cvt_pk_bf16_f32 v170, v90, v91
	v_cvt_pk_bf16_f32 v171, v92, v93
	v_cvt_pk_bf16_f32 v172, v94, v95
	s_waitcnt lgkmcnt(14)
	v_mfma_f32_32x32x16_bf16 v[50:65], v[194:197], v[134:137], v[50:65]
	ds_read_b64_tr_b16 v[194:195], v150 offset:53760
	ds_read_b64_tr_b16 v[196:197], v150 offset:55808
	v_cvt_pk_bf16_f32 v173, v96, v97
	v_permlane32_swap_b32_e32 v166, v168
	v_permlane32_swap_b32_e32 v167, v169
	v_permlane32_swap_b32_e32 v170, v172
	v_permlane32_swap_b32_e32 v171, v173
	s_waitcnt lgkmcnt(6)
	v_mfma_f32_32x32x16_bf16 v[2:17], v[158:161], v[182:185], v[2:17]
	ds_read_b128 v[182:185], v140 offset:16384
	v_max3_f32 v177, v34, v35, v36
	v_max3_f32 v178, v37, v38, v39
	v_max3_f32 v177, v177, v40, v41
	s_waitcnt lgkmcnt(5)
	v_mfma_f32_32x32x16_bf16 v[18:33], v[158:161], v[186:189], v[18:33]
	ds_read_b128 v[186:189], v140 offset:24576
	v_max3_f32 v178, v178, v42, v43
	v_max3_f32 v177, v177, v44, v45
	v_max3_f32 v178, v178, v46, v47
	v_max3_f32 v177, v177, v48, v49
	v_max3_f32 v178, v178, v50, v51
	v_max3_f32 v177, v177, v52, v53
	s_waitcnt lgkmcnt(4)
	v_mfma_f32_32x32x16_bf16 v[2:17], v[162:165], v[190:193], v[2:17]
	ds_read_b128 v[190:193], v141 offset:16384
	v_max3_f32 v178, v178, v54, v55
	v_max3_f32 v177, v177, v56, v57
	v_max3_f32 v178, v178, v58, v59
	v_max3_f32 v177, v177, v60, v61
	v_max3_f32 v178, v178, v62, v63
	v_max3_f32 v177, v177, v64, v65
	s_waitcnt lgkmcnt(3)
	v_mfma_f32_32x32x16_bf16 v[18:33], v[162:165], v[194:197], v[18:33]
	ds_read_b128 v[194:197], v141 offset:24576
	v_max_f32_e32 v177, v177, v178
	v_mov_b32_e32 v178, v177
	s_nop 1
	v_permlane32_swap_b32_e32 v177, v178
	v_max_f32_e32 v177, v177, v178
	v_cmp_ge_f32_e32 vcc, 0x4138aa3b, v177
	s_cmp_eq_u64 vcc, exec
	s_cbranch_scc0 .Lat_rare1_14

; __device__ __forceinline__ void attn_item(const bf16_t* __restrict__ Qb, const bf16_t* __restrict__ Kn, const bf16_t* __restrict__ Kr, const bf16_t* __restrict__ Vh,
;                                           const float* __restrict__ csq, bf16_t* __restrict__ Ob, int seq, char* lds) {
;     ...
;   for (int j = 1; j + 1 < NT; j += 2) {
;     STEP(pB0, pB1, alB, pA0, pA1, alA, j, true);
;     STEP(pA0, pA1, alA, pB0, pB1, alB, j + 1, true);
;   }
;   STEP(pB0, pB1, alB, pA0, pA1, alA, NT - 1, false);
.Lat_rr_16:
	s_waitcnt lgkmcnt(0)
	s_barrier
	s_add_i32 s8, s8, 1
	s_cmp_lt_u32 s8, 30
	s_cbranch_scc1 .Lat_loop
	ds_read_b128 v[198:201], v142 offset:16384
	ds_read_b128 v[202:205], v142 offset:24576
	ds_read_b128 v[206:209], v143 offset:16384
	ds_read_b128 v[210:213], v143 offset:24576
	s_add_i32 m0, s6, 0
	s_mov_b64 exec, s[20:21]
	global_load_lds_dwordx4 v146, s[14:15]
	s_add_i32 m0, s6, 1024
	s_mov_b64 exec, s[22:23]
	global_load_lds_dwordx4 v147, s[14:15]
	s_add_i32 m0, s7, 32768
	s_mov_b64 exec, -1
	global_load_lds_dwordx4 v149, s[14:15]
	v_add_u32_e32 v146, v146, v148
	v_add_u32_e32 v147, v147, v148
	v_add_u32_e32 v149, 0x38000, v149
	v_mfma_f32_32x32x16_bf16 v[66:81], v[182:185], v[114:117], v[98:113]
	ds_read_b128 v[182:185], v144 offset:16384
	v_exp_f32_e32 v50, v50
	v_exp_f32_e32 v51, v51
	v_exp_f32_e32 v52, v52
	v_exp_f32_e32 v53, v53
	v_exp_f32_e32 v54, v54
	v_mfma_f32_32x32x16_bf16 v[82:97], v[186:189], v[114:117], v[98:113]
	ds_read_b128 v[186:189], v144 offset:24576
	v_exp_f32_e32 v55, v55
	v_exp_f32_e32 v56, v56
	v_exp_f32_e32 v57, v57
	v_exp_f32_e32 v58, v58
	v_exp_f32_e32 v59, v59
	v_mfma_f32_32x32x16_bf16 v[66:81], v[190:193], v[118:121], v[66:81]
	ds_read_b128 v[190:193], v145 offset:16384
	v_exp_f32_e32 v60, v60
	v_exp_f32_e32 v61, v61
	v_exp_f32_e32 v62, v62
	v_exp_f32_e32 v63, v63
	v_exp_f32_e32 v64, v64
	v_mfma_f32_32x32x16_bf16 v[82:97], v[194:197], v[118:121], v[82:97]
	ds_read_b128 v[194:197], v145 offset:24576
	v_exp_f32_e32 v65, v65
	v_cvt_pk_bf16_f32 v158, v34, v35
	v_cvt_pk_bf16_f32 v159, v36, v37
	v_cvt_pk_bf16_f32 v160, v38, v39
	v_cvt_pk_bf16_f32 v161, v40, v41
	s_waitcnt lgkmcnt(7)
	v_mfma_f32_32x32x16_bf16 v[66:81], v[198:201], v[122:125], v[66:81]
	ds_read_b64_tr_b16 v[198:199], v150 offset:8192
	ds_read_b64_tr_b16 v[200:201], v150 offset:10240
	v_cvt_pk_bf16_f32 v162, v42, v43
	v_cvt_pk_bf16_f32 v163, v44, v45
	v_cvt_pk_bf16_f32 v164, v46, v47
	v_cvt_pk_bf16_f32 v165, v48, v49
	v_permlane32_swap_b32_e32 v158, v160
	s_waitcnt lgkmcnt(8)
	v_mfma_f32_32x32x16_bf16 v[82:97], v[202:205], v[122:125], v[82:97]
	ds_read_b64_tr_b16 v[202:203], v150 offset:8704
	ds_read_b64_tr_b16 v[204:205], v150 offset:10752
	v_permlane32_swap_b32_e32 v159, v161
	v_permlane32_swap_b32_e32 v162, v164
	v_permlane32_swap_b32_e32 v163, v165
	v_add_f32_e32 v214, v214, v50
	v_add_f32_e32 v215, v215, v51
	s_waitcnt lgkmcnt(9)
	v_mfma_f32_32x32x16_bf16 v[66:81], v[206:209], v[126:129], v[66:81]
	ds_read_b64_tr_b16 v[206:207], v150 offset:12288
	ds_read_b64_tr_b16 v[208:209], v150 offset:14336
	v_add_f32_e32 v216, v216, v52
	v_add_f32_e32 v217, v217, v53
	v_add_f32_e32 v214, v214, v54
	v_add_f32_e32 v215, v215, v55
	v_add_f32_e32 v216, v216, v56
	s_waitcnt lgkmcnt(10)
	v_mfma_f32_32x32x16_bf16 v[82:97], v[210:213], v[126:129], v[82:97]
	ds_read_b64_tr_b16 v[210:211], v150 offset:12800
	ds_read_b64_tr_b16 v[212:213], v150 offset:14848
	v_add_f32_e32 v217, v217, v57
	v_add_f32_e32 v214, v214, v58
	v_add_f32_e32 v215, v215, v59
	v_add_f32_e32 v216, v216, v60
	v_add_f32_e32 v217, v217, v61
	s_waitcnt lgkmcnt(11)
	v_mfma_f32_32x32x16_bf16 v[66:81], v[182:185], v[130:133], v[66:81]
	ds_read_b64_tr_b16 v[182:183], v150 offset:0
	ds_read_b64_tr_b16 v[184:185], v150 offset:2048
	v_add_f32_e32 v214, v214, v62
	v_add_f32_e32 v215, v215, v63
	v_add_f32_e32 v216, v216, v64
	v_add_f32_e32 v217, v217, v65
	v_add_f32_e32 v214, v214, v215
	s_waitcnt lgkmcnt(12)
	v_mfma_f32_32x32x16_bf16 v[82:97], v[186:189], v[130:133], v[82:97]
	ds_read_b64_tr_b16 v[186:187], v150 offset:512
	ds_read_b64_tr_b16 v[188:189], v150 offset:2560
	v_add_f32_e32 v216, v216, v217
	v_add_f32_e32 v214, v214, v216
	v_add_f32_e32 v174, v174, v214
	v_cvt_pk_bf16_f32 v166, v50, v51
	v_cvt_pk_bf16_f32 v167, v52, v53
	s_waitcnt lgkmcnt(13)
	v_mfma_f32_32x32x16_bf16 v[66:81], v[190:193], v[134:137], v[66:81]
	ds_read_b64_tr_b16 v[190:191], v150 offset:4096
	ds_read_b64_tr_b16 v[192:193], v150 offset:6144
	v_cvt_pk_bf16_f32 v168, v54, v55
	v_cvt_pk_bf16_f32 v169, v56, v57
	v_cvt_pk_bf16_f32 v170, v58, v59
	v_cvt_pk_bf16_f32 v171, v60, v61
	v_cvt_pk_bf16_f32 v172, v62, v63
	s_waitcnt lgkmcnt(14)
	v_mfma_f32_32x32x16_bf16 v[82:97], v[194:197], v[134:137], v[82:97]
	ds_read_b64_tr_b16 v[194:195], v150 offset:4608
	ds_read_b64_tr_b16 v[196:197], v150 offset:6656
	v_cvt_pk_bf16_f32 v173, v64, v65
	v_permlane32_swap_b32_e32 v166, v168
	v_permlane32_swap_b32_e32 v167, v169
	v_permlane32_swap_b32_e32 v170, v172
	v_permlane32_swap_b32_e32 v171, v173
	s_waitcnt lgkmcnt(6)
	v_mfma_f32_32x32x16_bf16 v[2:17], v[158:161], v[182:185], v[2:17]
	ds_read_b128 v[182:185], v140 offset:32768
	v_max3_f32 v177, v66, v67, v68
	v_max3_f32 v178, v69, v70, v71
	v_max3_f32 v177, v177, v72, v73
	s_waitcnt lgkmcnt(5)
	v_mfma_f32_32x32x16_bf16 v[18:33], v[158:161], v[186:189], v[18:33]
	ds_read_b128 v[186:189], v140 offset:40960
	v_max3_f32 v178, v178, v74, v75
	v_max3_f32 v177, v177, v76, v77
	v_max3_f32 v178, v178, v78, v79
	v_max3_f32 v177, v177, v80, v81
	v_max3_f32 v178, v178, v82, v83
	v_max3_f32 v177, v177, v84, v85
	s_waitcnt lgkmcnt(4)
	v_mfma_f32_32x32x16_bf16 v[2:17], v[162:165], v[190:193], v[2:17]
	ds_read_b128 v[190:193], v141 offset:32768
	v_max3_f32 v178, v178, v86, v87
	v_max3_f32 v177, v177, v88, v89
	v_max3_f32 v178, v178, v90, v91
	v_max3_f32 v177, v177, v92, v93
	v_max3_f32 v178, v178, v94, v95
	v_max3_f32 v177, v177, v96, v97
	s_waitcnt lgkmcnt(3)
	v_mfma_f32_32x32x16_bf16 v[18:33], v[162:165], v[194:197], v[18:33]
	ds_read_b128 v[194:197], v141 offset:40960
	v_max_f32_e32 v177, v177, v178
	v_mov_b32_e32 v178, v177
	s_nop 1
	v_permlane32_swap_b32_e32 v177, v178
	v_max_f32_e32 v177, v177, v178
	v_cmp_ge_f32_e32 vcc, 0x4138aa3b, v177
	s_cmp_eq_u64 vcc, exec
	s_cbranch_scc0 .Lat_rare1_18

; __device__ __forceinline__ void finishSM(f32x16& p0, f32x16& p1, float alpha, float& l_reg, bf16x8& pa0, bf16x8& pa1, bf16x8& pa2, bf16x8& pa3) {
; #pragma unroll
;   for (int r = 0; r < 16; ++r) p1[r] = __builtin_amdgcn_exp2f(p1[r]);
;   float ps = 0;
; #pragma unroll
;   for (int r = 0; r < 16; ++r) ps += p0[r];
; #pragma unroll
;   for (int r = 0; r < 16; ++r) ps += p1[r];
;   { auto rr = __builtin_amdgcn_permlane32_swap(__float_as_uint(ps), __float_as_uint(ps), false, false);
;     ps = __uint_as_float(rr[0]) + __uint_as_float(rr[1]); }
;   l_reg = l_reg * alpha + ps;
;     ...
;   PK4(p0, 0, pa0); PK4(p0, 8, pa1); PK4(p1, 0, pa2); PK4(p1, 8, pa3);
;     ...
; }
; __device__ __forceinline__ void qkt(f32x16& p0, f32x16& p1, const bf16_t* Ks, const bf16x8* qr, const f32x16& negm, int r32, int hi) {
;   p0 = negm; p1 = negm;
; #pragma unroll
;   for (int d0 = 0; d0 < 6; ++d0) { int cb = (d0 * 16 + hi * 8) * 2;
;     bf16x8 b0 = *reinterpret_cast<const bf16x8*>((const char*)Ks + KSWZ(r32, cb));
;     bf16x8 b1 = *reinterpret_cast<const bf16x8*>((const char*)Ks + KSWZ(32 + r32, cb));
;     p0 = __builtin_amdgcn_mfma_f32_32x32x16_bf16(b0, qr[d0], p0, 0, 0, 0);
;     p1 = __builtin_amdgcn_mfma_f32_32x32x16_bf16(b1, qr[d0], p1, 0, 0, 0); }
; }
; __device__ __forceinline__ int v_st(int k, int c) { const int kk = (k & ~0xC) | ((k & 4) << 1) | ((k & 8) >> 1); return ((kk >> 3) * 4 + (c >> 5)) * 512 + ((kk & 7) * 32 + (c & 31)) * 2; }
; __device__ __forceinline__ int v_rd_base(int lane) { return ((lane & 3) << 3) | (((lane >> 2) & 3) << 6) | (((lane >> 4) & 1) << 5) | (((lane >> 5) & 1) << 8); }
; template <int OFF> __device__ __forceinline__ s16x4 tr_read(int vb) {
;   s16x4 r; asm volatile("ds_read_b64_tr_b16 %0, %1 offset:%2" : "=&v"(r) : "v"(vb), "i"(OFF) : "memory"); return r;
; }
; template <int D0> __device__ __forceinline__ void pv_one(f32x16& od, int vb, bf16x8 pa0, bf16x8 pa1, bf16x8 pa2, bf16x8 pa3) {
;   const s16x4 l0 = tr_read<v_rd_off(D0, 0, 0)>(vb), h0 = tr_read<v_rd_off(D0, 0, 1)>(vb), l1 = tr_read<v_rd_off(D0, 1, 0)>(vb), h1 = tr_read<v_rd_off(D0, 1, 1)>(vb);
;   const s16x4 l2 = tr_read<v_rd_off(D0, 2, 0)>(vb), h2 = tr_read<v_rd_off(D0, 2, 1)>(vb), l3 = tr_read<v_rd_off(D0, 3, 0)>(vb), h3 = tr_read<v_rd_off(D0, 3, 1)>(vb);
;   asm volatile("s_waitcnt lgkmcnt(0)" ::: "memory"); SBAR();
;     ...
;   od = __builtin_amdgcn_mfma_f32_32x32x16_bf16(pa0, PK(l0, h0), od, 0, 0, 0);
.Lat_rr_32:
	s_waitcnt lgkmcnt(0)
	s_barrier
	ds_read_b128 v[198:201], v142 offset:16384
	ds_read_b128 v[202:205], v142 offset:24576
	ds_read_b128 v[206:209], v143 offset:16384
	ds_read_b128 v[210:213], v143 offset:24576
	s_add_i32 m0, s7, 32768
	s_mov_b64 exec, -1
	global_load_lds_dwordx4 v149, s[14:15]
	v_add_u32_e32 v149, 0x38000, v149
	v_mfma_f32_32x32x16_bf16 v[66:81], v[182:185], v[114:117], v[98:113]
	ds_read_b128 v[182:185], v144 offset:16384
	v_exp_f32_e32 v50, v50
	v_exp_f32_e32 v51, v51
	v_exp_f32_e32 v52, v52
	v_exp_f32_e32 v53, v53
	v_exp_f32_e32 v54, v54
	v_mfma_f32_32x32x16_bf16 v[82:97], v[186:189], v[114:117], v[98:113]
	ds_read_b128 v[186:189], v144 offset:24576
	v_exp_f32_e32 v55, v55
	v_exp_f32_e32 v56, v56
	v_exp_f32_e32 v57, v57
	v_exp_f32_e32 v58, v58
	v_exp_f32_e32 v59, v59
	v_mfma_f32_32x32x16_bf16 v[66:81], v[190:193], v[118:121], v[66:81]
	ds_read_b128 v[190:193], v145 offset:16384
	v_exp_f32_e32 v60, v60
	v_exp_f32_e32 v61, v61
	v_exp_f32_e32 v62, v62
	v_exp_f32_e32 v63, v63
	v_exp_f32_e32 v64, v64
	v_mfma_f32_32x32x16_bf16 v[82:97], v[194:197], v[118:121], v[82:97]
	ds_read_b128 v[194:197], v145 offset:24576
	v_exp_f32_e32 v65, v65
	v_cvt_pk_bf16_f32 v158, v34, v35
	v_cvt_pk_bf16_f32 v159, v36, v37
	v_cvt_pk_bf16_f32 v160, v38, v39
	v_cvt_pk_bf16_f32 v161, v40, v41
	s_waitcnt lgkmcnt(7)
	v_mfma_f32_32x32x16_bf16 v[66:81], v[198:201], v[122:125], v[66:81]
	ds_read_b64_tr_b16 v[198:199], v150 offset:8192
	ds_read_b64_tr_b16 v[200:201], v150 offset:10240
	v_cvt_pk_bf16_f32 v162, v42, v43
	v_cvt_pk_bf16_f32 v163, v44, v45
	v_cvt_pk_bf16_f32 v164, v46, v47
	v_cvt_pk_bf16_f32 v165, v48, v49
	v_permlane32_swap_b32_e32 v158, v160
	s_waitcnt lgkmcnt(8)
	v_mfma_f32_32x32x16_bf16 v[82:97], v[202:205], v[122:125], v[82:97]
	ds_read_b64_tr_b16 v[202:203], v150 offset:8704
	ds_read_b64_tr_b16 v[204:205], v150 offset:10752
	v_permlane32_swap_b32_e32 v159, v161
	v_permlane32_swap_b32_e32 v162, v164
	v_permlane32_swap_b32_e32 v163, v165
	v_add_f32_e32 v214, v214, v50
	v_add_f32_e32 v215, v215, v51
	s_waitcnt lgkmcnt(9)
	v_mfma_f32_32x32x16_bf16 v[66:81], v[206:209], v[126:129], v[66:81]
	ds_read_b64_tr_b16 v[206:207], v150 offset:12288
	ds_read_b64_tr_b16 v[208:209], v150 offset:14336
	v_add_f32_e32 v216, v216, v52
	v_add_f32_e32 v217, v217, v53
	v_add_f32_e32 v214, v214, v54
	v_add_f32_e32 v215, v215, v55
	v_add_f32_e32 v216, v216, v56
	s_waitcnt lgkmcnt(10)
	v_mfma_f32_32x32x16_bf16 v[82:97], v[210:213], v[126:129], v[82:97]
	ds_read_b64_tr_b16 v[210:211], v150 offset:12800
	ds_read_b64_tr_b16 v[212:213], v150 offset:14848
	v_add_f32_e32 v217, v217, v57
	v_add_f32_e32 v214, v214, v58
	v_add_f32_e32 v215, v215, v59
	v_add_f32_e32 v216, v216, v60
	v_add_f32_e32 v217, v217, v61
	s_waitcnt lgkmcnt(11)
	v_mfma_f32_32x32x16_bf16 v[66:81], v[182:185], v[130:133], v[66:81]
	ds_read_b64_tr_b16 v[182:183], v150 offset:0
	ds_read_b64_tr_b16 v[184:185], v150 offset:2048
	v_add_f32_e32 v214, v214, v62
	v_add_f32_e32 v215, v215, v63
	v_add_f32_e32 v216, v216, v64
	v_add_f32_e32 v217, v217, v65
	v_add_f32_e32 v214, v214, v215
	s_waitcnt lgkmcnt(12)
	v_mfma_f32_32x32x16_bf16 v[82:97], v[186:189], v[130:133], v[82:97]
	ds_read_b64_tr_b16 v[186:187], v150 offset:512
	ds_read_b64_tr_b16 v[188:189], v150 offset:2560
	v_add_f32_e32 v216, v216, v217
	v_add_f32_e32 v214, v214, v216
	v_add_f32_e32 v174, v174, v214
	v_cvt_pk_bf16_f32 v166, v50, v51
	v_cvt_pk_bf16_f32 v167, v52, v53
	s_waitcnt lgkmcnt(13)
	v_mfma_f32_32x32x16_bf16 v[66:81], v[190:193], v[134:137], v[66:81]
	ds_read_b64_tr_b16 v[190:191], v150 offset:4096
	ds_read_b64_tr_b16 v[192:193], v150 offset:6144
	v_cvt_pk_bf16_f32 v168, v54, v55
	v_cvt_pk_bf16_f32 v169, v56, v57
	v_cvt_pk_bf16_f32 v170, v58, v59
	v_cvt_pk_bf16_f32 v171, v60, v61
	v_cvt_pk_bf16_f32 v172, v62, v63
	s_waitcnt lgkmcnt(14)
	v_mfma_f32_32x32x16_bf16 v[82:97], v[194:197], v[134:137], v[82:97]
	ds_read_b64_tr_b16 v[194:195], v150 offset:4608
	ds_read_b64_tr_b16 v[196:197], v150 offset:6656
	v_cvt_pk_bf16_f32 v173, v64, v65
	v_permlane32_swap_b32_e32 v166, v168
	v_permlane32_swap_b32_e32 v167, v169
	v_permlane32_swap_b32_e32 v170, v172
	v_permlane32_swap_b32_e32 v171, v173
	s_waitcnt lgkmcnt(6)
	v_mfma_f32_32x32x16_bf16 v[2:17], v[158:161], v[182:185], v[2:17]
	ds_read_b128 v[182:185], v140 offset:32768
	v_max3_f32 v177, v66, v67, v68
	v_max3_f32 v178, v69, v70, v71
	v_max3_f32 v177, v177, v72, v73
	s_waitcnt lgkmcnt(5)
	v_mfma_f32_32x32x16_bf16 v[18:33], v[158:161], v[186:189], v[18:33]
	ds_read_b128 v[186:189], v140 offset:40960
	v_max3_f32 v178, v178, v74, v75
	v_max3_f32 v177, v177, v76, v77
	v_max3_f32 v178, v178, v78, v79
	v_max3_f32 v177, v177, v80, v81
	v_max3_f32 v178, v178, v82, v83
	v_max3_f32 v177, v177, v84, v85
	s_waitcnt lgkmcnt(4)
	v_mfma_f32_32x32x16_bf16 v[2:17], v[162:165], v[190:193], v[2:17]
	ds_read_b128 v[190:193], v141 offset:32768
	v_max3_f32 v178, v178, v86, v87
	v_max3_f32 v177, v177, v88, v89
	v_max3_f32 v178, v178, v90, v91
	v_max3_f32 v177, v177, v92, v93
	v_max3_f32 v178, v178, v94, v95
	v_max3_f32 v177, v177, v96, v97
	s_waitcnt lgkmcnt(3)
	v_mfma_f32_32x32x16_bf16 v[18:33], v[162:165], v[194:197], v[18:33]
	ds_read_b128 v[194:197], v141 offset:40960
	v_max_f32_e32 v177, v177, v178
	v_mov_b32_e32 v178, v177
	s_nop 1
	v_permlane32_swap_b32_e32 v177, v178
	v_max_f32_e32 v177, v177, v178
	v_cmp_ge_f32_e32 vcc, 0x4138aa3b, v177
	s_cmp_eq_u64 vcc, exec
	s_cbranch_scc0 .Lat_rare1_34
; __device__ __forceinline__ void finishSM(f32x16& p0, f32x16& p1, float alpha, float& l_reg, bf16x8& pa0, bf16x8& pa1, bf16x8& pa2, bf16x8& pa3) {
; #pragma unroll
;   for (int r = 0; r < 16; ++r) p1[r] = __builtin_amdgcn_exp2f(p1[r]);
;   float ps = 0;
; #pragma unroll
;   for (int r = 0; r < 16; ++r) ps += p0[r];
; #pragma unroll
;   for (int r = 0; r < 16; ++r) ps += p1[r];
;   { auto rr = __builtin_amdgcn_permlane32_swap(__float_as_uint(ps), __float_as_uint(ps), false, false);
;     ps = __uint_as_float(rr[0]) + __uint_as_float(rr[1]); }
;   l_reg = l_reg * alpha + ps;
;     ...
;   PK4(p0, 0, pa0); PK4(p0, 8, pa1); PK4(p1, 0, pa2); PK4(p1, 8, pa3);
;     ...
; }
; __device__ __forceinline__ void qkt(f32x16& p0, f32x16& p1, const bf16_t* Ks, const bf16x8* qr, const f32x16& negm, int r32, int hi) {
;   p0 = negm; p1 = negm;
; #pragma unroll
;   for (int d0 = 0; d0 < 6; ++d0) { int cb = (d0 * 16 + hi * 8) * 2;
;     bf16x8 b0 = *reinterpret_cast<const bf16x8*>((const char*)Ks + KSWZ(r32, cb));
;     bf16x8 b1 = *reinterpret_cast<const bf16x8*>((const char*)Ks + KSWZ(32 + r32, cb));
;     p0 = __builtin_amdgcn_mfma_f32_32x32x16_bf16(b0, qr[d0], p0, 0, 0, 0);
;     p1 = __builtin_amdgcn_mfma_f32_32x32x16_bf16(b1, qr[d0], p1, 0, 0, 0); }
; }
; __device__ __forceinline__ int v_st(int k, int c) { const int kk = (k & ~0xC) | ((k & 4) << 1) | ((k & 8) >> 1); return ((kk >> 3) * 4 + (c >> 5)) * 512 + ((kk & 7) * 32 + (c & 31)) * 2; }
; __device__ __forceinline__ int v_rd_base(int lane) { return ((lane & 3) << 3) | (((lane >> 2) & 3) << 6) | (((lane >> 4) & 1) << 5) | (((lane >> 5) & 1) << 8); }
; template <int OFF> __device__ __forceinline__ s16x4 tr_read(int vb) {
;   s16x4 r; asm volatile("ds_read_b64_tr_b16 %0, %1 offset:%2" : "=&v"(r) : "v"(vb), "i"(OFF) : "memory"); return r;
; }
; template <int D0> __device__ __forceinline__ void pv_one(f32x16& od, int vb, bf16x8 pa0, bf16x8 pa1, bf16x8 pa2, bf16x8 pa3) {
;   const s16x4 l0 = tr_read<v_rd_off(D0, 0, 0)>(vb), h0 = tr_read<v_rd_off(D0, 0, 1)>(vb), l1 = tr_read<v_rd_off(D0, 1, 0)>(vb), h1 = tr_read<v_rd_off(D0, 1, 1)>(vb);
;   const s16x4 l2 = tr_read<v_rd_off(D0, 2, 0)>(vb), h2 = tr_read<v_rd_off(D0, 2, 1)>(vb), l3 = tr_read<v_rd_off(D0, 3, 0)>(vb), h3 = tr_read<v_rd_off(D0, 3, 1)>(vb);
;   asm volatile("s_waitcnt lgkmcnt(0)" ::: "memory"); SBAR();
;     ...
;   od = __builtin_amdgcn_mfma_f32_32x32x16_bf16(pa0, PK(l0, h0), od, 0, 0, 0);
.Lat_ri_33:
	v_mfma_f32_32x32x16_bf16 v[2:17], v[166:169], v[198:201], v[2:17]
	v_exp_f32_e32 v66, v66
	v_exp_f32_e32 v67, v67
	v_exp_f32_e32 v68, v68
	v_exp_f32_e32 v69, v69
	v_exp_f32_e32 v70, v70
	v_exp_f32_e32 v71, v71
	v_exp_f32_e32 v72, v72
	v_mfma_f32_32x32x16_bf16 v[18:33], v[166:169], v[202:205], v[18:33]
	v_exp_f32_e32 v73, v73
	v_exp_f32_e32 v74, v74
	v_exp_f32_e32 v75, v75
	v_exp_f32_e32 v76, v76
	v_exp_f32_e32 v77, v77
	v_exp_f32_e32 v78, v78
	v_exp_f32_e32 v79, v79
	v_mfma_f32_32x32x16_bf16 v[2:17], v[170:173], v[206:209], v[2:17]
	v_exp_f32_e32 v80, v80
	v_exp_f32_e32 v81, v81
	v_add_f32_e32 v214, v66, v70
	v_add_f32_e32 v215, v67, v71
	v_add_f32_e32 v216, v68, v72
	v_add_f32_e32 v217, v69, v73
	v_add_f32_e32 v214, v214, v74
	v_mfma_f32_32x32x16_bf16 v[18:33], v[170:173], v[210:213], v[18:33]
	v_add_f32_e32 v215, v215, v75
	v_add_f32_e32 v216, v216, v76
	v_add_f32_e32 v217, v217, v77
	v_add_f32_e32 v214, v214, v78
	v_add_f32_e32 v215, v215, v79
	v_add_f32_e32 v216, v216, v80
	v_add_f32_e32 v217, v217, v81
	s_waitcnt vmcnt(1)
	s_cmp_lg_u32 s9, 0
	s_cbranch_scc1 .Lat_rare2_35
.Lat_rr_36:
	s_waitcnt lgkmcnt(0)
	s_barrier
	ds_read_b128 v[198:201], v142 offset:32768
	ds_read_b128 v[202:205], v142 offset:40960
	ds_read_b128 v[206:209], v143 offset:32768
	ds_read_b128 v[210:213], v143 offset:40960
	s_add_i32 m0, s7, 49152
	s_mov_b64 exec, -1
	global_load_lds_dwordx4 v149, s[14:15]
	v_add_u32_e32 v149, 0x38000, v149
	v_mfma_f32_32x32x16_bf16 v[34:49], v[182:185], v[114:117], v[98:113]
	ds_read_b128 v[182:185], v144 offset:32768
	v_exp_f32_e32 v82, v82
	v_exp_f32_e32 v83, v83
	v_exp_f32_e32 v84, v84
	v_exp_f32_e32 v85, v85
	v_exp_f32_e32 v86, v86
	v_mfma_f32_32x32x16_bf16 v[50:65], v[186:189], v[114:117], v[98:113]
	ds_read_b128 v[186:189], v144 offset:40960
	v_exp_f32_e32 v87, v87
	v_exp_f32_e32 v88, v88
	v_exp_f32_e32 v89, v89
	v_exp_f32_e32 v90, v90
	v_exp_f32_e32 v91, v91
	v_mfma_f32_32x32x16_bf16 v[34:49], v[190:193], v[118:121], v[34:49]
	ds_read_b128 v[190:193], v145 offset:32768
	v_exp_f32_e32 v92, v92
	v_exp_f32_e32 v93, v93
	v_exp_f32_e32 v94, v94
	v_exp_f32_e32 v95, v95
	v_exp_f32_e32 v96, v96
	v_mfma_f32_32x32x16_bf16 v[50:65], v[194:197], v[118:121], v[50:65]
	ds_read_b128 v[194:197], v145 offset:40960
	v_exp_f32_e32 v97, v97
	v_cvt_pk_bf16_f32 v158, v66, v67
	v_cvt_pk_bf16_f32 v159, v68, v69
	v_cvt_pk_bf16_f32 v160, v70, v71
	v_cvt_pk_bf16_f32 v161, v72, v73
	s_waitcnt lgkmcnt(7)
	v_mfma_f32_32x32x16_bf16 v[34:49], v[198:201], v[122:125], v[34:49]
	ds_read_b64_tr_b16 v[198:199], v150 offset:24576
	ds_read_b64_tr_b16 v[200:201], v150 offset:26624
	v_cvt_pk_bf16_f32 v162, v74, v75
	v_cvt_pk_bf16_f32 v163, v76, v77
	v_cvt_pk_bf16_f32 v164, v78, v79
	v_cvt_pk_bf16_f32 v165, v80, v81
	v_permlane32_swap_b32_e32 v158, v160
	s_waitcnt lgkmcnt(8)
	v_mfma_f32_32x32x16_bf16 v[50:65], v[202:205], v[122:125], v[50:65]
	ds_read_b64_tr_b16 v[202:203], v150 offset:25088
	ds_read_b64_tr_b16 v[204:205], v150 offset:27136
	v_permlane32_swap_b32_e32 v159, v161
	v_permlane32_swap_b32_e32 v162, v164
	v_permlane32_swap_b32_e32 v163, v165
	v_add_f32_e32 v214, v214, v82
	v_add_f32_e32 v215, v215, v83
	s_waitcnt lgkmcnt(9)
	v_mfma_f32_32x32x16_bf16 v[34:49], v[206:209], v[126:129], v[34:49]
	ds_read_b64_tr_b16 v[206:207], v150 offset:28672
	ds_read_b64_tr_b16 v[208:209], v150 offset:30720
	v_add_f32_e32 v216, v216, v84
	v_add_f32_e32 v217, v217, v85
	v_add_f32_e32 v214, v214, v86
	v_add_f32_e32 v215, v215, v87
	v_add_f32_e32 v216, v216, v88
	s_waitcnt lgkmcnt(10)
	v_mfma_f32_32x32x16_bf16 v[50:65], v[210:213], v[126:129], v[50:65]
	ds_read_b64_tr_b16 v[210:211], v150 offset:29184
	ds_read_b64_tr_b16 v[212:213], v150 offset:31232
	v_add_f32_e32 v217, v217, v89
	v_add_f32_e32 v214, v214, v90
	v_add_f32_e32 v215, v215, v91
	v_add_f32_e32 v216, v216, v92
	v_add_f32_e32 v217, v217, v93
	s_waitcnt lgkmcnt(11)
	v_mfma_f32_32x32x16_bf16 v[34:49], v[182:185], v[130:133], v[34:49]
	ds_read_b64_tr_b16 v[182:183], v150 offset:16384
	ds_read_b64_tr_b16 v[184:185], v150 offset:18432
	v_add_f32_e32 v214, v214, v94
	v_add_f32_e32 v215, v215, v95
	v_add_f32_e32 v216, v216, v96
	v_add_f32_e32 v217, v217, v97
	v_add_f32_e32 v214, v214, v215
	s_waitcnt lgkmcnt(12)
	v_mfma_f32_32x32x16_bf16 v[50:65], v[186:189], v[130:133], v[50:65]
	ds_read_b64_tr_b16 v[186:187], v150 offset:16896
	ds_read_b64_tr_b16 v[188:189], v150 offset:18944
	v_add_f32_e32 v216, v216, v217
	v_add_f32_e32 v214, v214, v216
	v_add_f32_e32 v174, v174, v214
	v_cvt_pk_bf16_f32 v166, v82, v83
	v_cvt_pk_bf16_f32 v167, v84, v85
	s_waitcnt lgkmcnt(13)
	v_mfma_f32_32x32x16_bf16 v[34:49], v[190:193], v[134:137], v[34:49]
	ds_read_b64_tr_b16 v[190:191], v150 offset:20480
	ds_read_b64_tr_b16 v[192:193], v150 offset:22528
	v_cvt_pk_bf16_f32 v168, v86, v87
	v_cvt_pk_bf16_f32 v169, v88, v89
	v_cvt_pk_bf16_f32 v170, v90, v91
	v_cvt_pk_bf16_f32 v171, v92, v93
	v_cvt_pk_bf16_f32 v172, v94, v95
	s_waitcnt lgkmcnt(14)
	v_mfma_f32_32x32x16_bf16 v[50:65], v[194:197], v[134:137], v[50:65]
	ds_read_b64_tr_b16 v[194:195], v150 offset:20992
	ds_read_b64_tr_b16 v[196:197], v150 offset:23040
	v_cvt_pk_bf16_f32 v173, v96, v97
	v_permlane32_swap_b32_e32 v166, v168
	v_permlane32_swap_b32_e32 v167, v169
	v_permlane32_swap_b32_e32 v170, v172
	v_permlane32_swap_b32_e32 v171, v173
	s_waitcnt lgkmcnt(6)
	v_mfma_f32_32x32x16_bf16 v[2:17], v[158:161], v[182:185], v[2:17]
	ds_read_b128 v[182:185], v140 offset:49152
	v_max3_f32 v177, v34, v35, v36
	v_max3_f32 v178, v37, v38, v39
	v_max3_f32 v177, v177, v40, v41
	s_waitcnt lgkmcnt(5)
	v_mfma_f32_32x32x16_bf16 v[18:33], v[158:161], v[186:189], v[18:33]
	ds_read_b128 v[186:189], v140 offset:57344
	v_max3_f32 v178, v178, v42, v43
	v_max3_f32 v177, v177, v44, v45
	v_max3_f32 v178, v178, v46, v47
	v_max3_f32 v177, v177, v48, v49
	v_max3_f32 v178, v178, v50, v51
	v_max3_f32 v177, v177, v52, v53
	s_waitcnt lgkmcnt(4)
	v_mfma_f32_32x32x16_bf16 v[2:17], v[162:165], v[190:193], v[2:17]
	ds_read_b128 v[190:193], v141 offset:49152
	v_max3_f32 v178, v178, v54, v55
	v_max3_f32 v177, v177, v56, v57
	v_max3_f32 v178, v178, v58, v59
	v_max3_f32 v177, v177, v60, v61
	v_max3_f32 v178, v178, v62, v63
	v_max3_f32 v177, v177, v64, v65
	s_waitcnt lgkmcnt(3)
	v_mfma_f32_32x32x16_bf16 v[18:33], v[162:165], v[194:197], v[18:33]
	ds_read_b128 v[194:197], v141 offset:57344
	v_max_f32_e32 v177, v177, v178
	v_mov_b32_e32 v178, v177
	s_nop 1
	v_permlane32_swap_b32_e32 v177, v178
	v_max_f32_e32 v177, v177, v178
	v_cmp_ge_f32_e32 vcc, 0x4138aa3b, v177
	s_cmp_eq_u64 vcc, exec
	s_cbranch_scc0 .Lat_rare1_38
; __device__ __forceinline__ void finishSM(f32x16& p0, f32x16& p1, float alpha, float& l_reg, bf16x8& pa0, bf16x8& pa1, bf16x8& pa2, bf16x8& pa3) {
; #pragma unroll
;   for (int r = 0; r < 16; ++r) p1[r] = __builtin_amdgcn_exp2f(p1[r]);
;   float ps = 0;
; #pragma unroll
;   for (int r = 0; r < 16; ++r) ps += p0[r];
; #pragma unroll
;   for (int r = 0; r < 16; ++r) ps += p1[r];
;   { auto rr = __builtin_amdgcn_permlane32_swap(__float_as_uint(ps), __float_as_uint(ps), false, false);
;     ps = __uint_as_float(rr[0]) + __uint_as_float(rr[1]); }
;   l_reg = l_reg * alpha + ps;
;     ...
;   PK4(p0, 0, pa0); PK4(p0, 8, pa1); PK4(p1, 0, pa2); PK4(p1, 8, pa3);
;     ...
; }
; __device__ __forceinline__ void qkt(f32x16& p0, f32x16& p1, const bf16_t* Ks, const bf16x8* qr, const f32x16& negm, int r32, int hi) {
;   p0 = negm; p1 = negm;
; #pragma unroll
;   for (int d0 = 0; d0 < 6; ++d0) { int cb = (d0 * 16 + hi * 8) * 2;
;     bf16x8 b0 = *reinterpret_cast<const bf16x8*>((const char*)Ks + KSWZ(r32, cb));
;     bf16x8 b1 = *reinterpret_cast<const bf16x8*>((const char*)Ks + KSWZ(32 + r32, cb));
;     p0 = __builtin_amdgcn_mfma_f32_32x32x16_bf16(b0, qr[d0], p0, 0, 0, 0);
;     p1 = __builtin_amdgcn_mfma_f32_32x32x16_bf16(b1, qr[d0], p1, 0, 0, 0); }
; }
; __device__ __forceinline__ int v_st(int k, int c) { const int kk = (k & ~0xC) | ((k & 4) << 1) | ((k & 8) >> 1); return ((kk >> 3) * 4 + (c >> 5)) * 512 + ((kk & 7) * 32 + (c & 31)) * 2; }
; __device__ __forceinline__ int v_rd_base(int lane) { return ((lane & 3) << 3) | (((lane >> 2) & 3) << 6) | (((lane >> 4) & 1) << 5) | (((lane >> 5) & 1) << 8); }
; template <int OFF> __device__ __forceinline__ s16x4 tr_read(int vb) {
;   s16x4 r; asm volatile("ds_read_b64_tr_b16 %0, %1 offset:%2" : "=&v"(r) : "v"(vb), "i"(OFF) : "memory"); return r;
; }
; template <int D0> __device__ __forceinline__ void pv_one(f32x16& od, int vb, bf16x8 pa0, bf16x8 pa1, bf16x8 pa2, bf16x8 pa3) {
;   const s16x4 l0 = tr_read<v_rd_off(D0, 0, 0)>(vb), h0 = tr_read<v_rd_off(D0, 0, 1)>(vb), l1 = tr_read<v_rd_off(D0, 1, 0)>(vb), h1 = tr_read<v_rd_off(D0, 1, 1)>(vb);
;   const s16x4 l2 = tr_read<v_rd_off(D0, 2, 0)>(vb), h2 = tr_read<v_rd_off(D0, 2, 1)>(vb), l3 = tr_read<v_rd_off(D0, 3, 0)>(vb), h3 = tr_read<v_rd_off(D0, 3, 1)>(vb);
;   asm volatile("s_waitcnt lgkmcnt(0)" ::: "memory"); SBAR();
;     ...
;   od = __builtin_amdgcn_mfma_f32_32x32x16_bf16(pa0, PK(l0, h0), od, 0, 0, 0);
.Lat_ri_37:
	v_mfma_f32_32x32x16_bf16 v[2:17], v[166:169], v[198:201], v[2:17]
	v_exp_f32_e32 v34, v34
	v_exp_f32_e32 v35, v35
	v_exp_f32_e32 v36, v36
	v_exp_f32_e32 v37, v37
	v_exp_f32_e32 v38, v38
	v_exp_f32_e32 v39, v39
	v_exp_f32_e32 v40, v40
	v_mfma_f32_32x32x16_bf16 v[18:33], v[166:169], v[202:205], v[18:33]
	v_exp_f32_e32 v41, v41
	v_exp_f32_e32 v42, v42
	v_exp_f32_e32 v43, v43
	v_exp_f32_e32 v44, v44
	v_exp_f32_e32 v45, v45
	v_exp_f32_e32 v46, v46
	v_exp_f32_e32 v47, v47
	v_mfma_f32_32x32x16_bf16 v[2:17], v[170:173], v[206:209], v[2:17]
	v_exp_f32_e32 v48, v48
	v_exp_f32_e32 v49, v49
	v_add_f32_e32 v214, v34, v38
	v_add_f32_e32 v215, v35, v39
	v_add_f32_e32 v216, v36, v40
	v_add_f32_e32 v217, v37, v41
	v_add_f32_e32 v214, v214, v42
	v_mfma_f32_32x32x16_bf16 v[18:33], v[170:173], v[210:213], v[18:33]
	v_add_f32_e32 v215, v215, v43
	v_add_f32_e32 v216, v216, v44
	v_add_f32_e32 v217, v217, v45
	v_add_f32_e32 v214, v214, v46
	v_add_f32_e32 v215, v215, v47
	v_add_f32_e32 v216, v216, v48
	v_add_f32_e32 v217, v217, v49
	s_waitcnt vmcnt(1)
	s_cmp_lg_u32 s9, 0
	s_cbranch_scc1 .Lat_rare2_39
.Lat_rr_40:
	s_waitcnt lgkmcnt(0)
	s_barrier
	ds_read_b128 v[198:201], v142 offset:49152
	ds_read_b128 v[202:205], v142 offset:57344
	ds_read_b128 v[206:209], v143 offset:49152
	ds_read_b128 v[210:213], v143 offset:57344
	v_mfma_f32_32x32x16_bf16 v[66:81], v[182:185], v[114:117], v[98:113]
	ds_read_b128 v[182:185], v144 offset:49152
	v_exp_f32_e32 v50, v50
	v_exp_f32_e32 v51, v51
	v_exp_f32_e32 v52, v52
	v_exp_f32_e32 v53, v53
	v_exp_f32_e32 v54, v54
	v_mfma_f32_32x32x16_bf16 v[82:97], v[186:189], v[114:117], v[98:113]
	ds_read_b128 v[186:189], v144 offset:57344
	v_exp_f32_e32 v55, v55
	v_exp_f32_e32 v56, v56
	v_exp_f32_e32 v57, v57
	v_exp_f32_e32 v58, v58
	v_exp_f32_e32 v59, v59
	v_mfma_f32_32x32x16_bf16 v[66:81], v[190:193], v[118:121], v[66:81]
	ds_read_b128 v[190:193], v145 offset:49152
	v_exp_f32_e32 v60, v60
	v_exp_f32_e32 v61, v61
	v_exp_f32_e32 v62, v62
	v_exp_f32_e32 v63, v63
	v_exp_f32_e32 v64, v64
	v_mfma_f32_32x32x16_bf16 v[82:97], v[194:197], v[118:121], v[82:97]
	ds_read_b128 v[194:197], v145 offset:57344
	v_exp_f32_e32 v65, v65
	v_cvt_pk_bf16_f32 v158, v34, v35
	v_cvt_pk_bf16_f32 v159, v36, v37
	v_cvt_pk_bf16_f32 v160, v38, v39
	v_cvt_pk_bf16_f32 v161, v40, v41
	s_waitcnt lgkmcnt(7)
	v_mfma_f32_32x32x16_bf16 v[66:81], v[198:201], v[122:125], v[66:81]
	ds_read_b64_tr_b16 v[198:199], v150 offset:40960
	ds_read_b64_tr_b16 v[200:201], v150 offset:43008
	v_cvt_pk_bf16_f32 v162, v42, v43
	v_cvt_pk_bf16_f32 v163, v44, v45
	v_cvt_pk_bf16_f32 v164, v46, v47
	v_cvt_pk_bf16_f32 v165, v48, v49
	v_permlane32_swap_b32_e32 v158, v160
	s_waitcnt lgkmcnt(8)
	v_mfma_f32_32x32x16_bf16 v[82:97], v[202:205], v[122:125], v[82:97]
	ds_read_b64_tr_b16 v[202:203], v150 offset:41472
	ds_read_b64_tr_b16 v[204:205], v150 offset:43520
	v_permlane32_swap_b32_e32 v159, v161
	v_permlane32_swap_b32_e32 v162, v164
	v_permlane32_swap_b32_e32 v163, v165
	v_add_f32_e32 v214, v214, v50
	v_add_f32_e32 v215, v215, v51
	s_waitcnt lgkmcnt(9)
	v_mfma_f32_32x32x16_bf16 v[66:81], v[206:209], v[126:129], v[66:81]
	ds_read_b64_tr_b16 v[206:207], v150 offset:45056
	ds_read_b64_tr_b16 v[208:209], v150 offset:47104
	v_add_f32_e32 v216, v216, v52
	v_add_f32_e32 v217, v217, v53
	v_add_f32_e32 v214, v214, v54
	v_add_f32_e32 v215, v215, v55
	v_add_f32_e32 v216, v216, v56
	s_waitcnt lgkmcnt(10)
	v_mfma_f32_32x32x16_bf16 v[82:97], v[210:213], v[126:129], v[82:97]
	ds_read_b64_tr_b16 v[210:211], v150 offset:45568
	ds_read_b64_tr_b16 v[212:213], v150 offset:47616
	v_add_f32_e32 v217, v217, v57
	v_add_f32_e32 v214, v214, v58
	v_add_f32_e32 v215, v215, v59
	v_add_f32_e32 v216, v216, v60
	v_add_f32_e32 v217, v217, v61
	s_waitcnt lgkmcnt(11)
	v_mfma_f32_32x32x16_bf16 v[66:81], v[182:185], v[130:133], v[66:81]
	ds_read_b64_tr_b16 v[182:183], v150 offset:32768
	ds_read_b64_tr_b16 v[184:185], v150 offset:34816
	v_add_f32_e32 v214, v214, v62
	v_add_f32_e32 v215, v215, v63
	v_add_f32_e32 v216, v216, v64
	v_add_f32_e32 v217, v217, v65
	v_add_f32_e32 v214, v214, v215
	s_waitcnt lgkmcnt(12)
	v_mfma_f32_32x32x16_bf16 v[82:97], v[186:189], v[130:133], v[82:97]
	ds_read_b64_tr_b16 v[186:187], v150 offset:33280
	ds_read_b64_tr_b16 v[188:189], v150 offset:35328
	v_add_f32_e32 v216, v216, v217
	v_add_f32_e32 v214, v214, v216
	v_add_f32_e32 v174, v174, v214
	v_cvt_pk_bf16_f32 v166, v50, v51
	v_cvt_pk_bf16_f32 v167, v52, v53
	s_waitcnt lgkmcnt(13)
	v_mfma_f32_32x32x16_bf16 v[66:81], v[190:193], v[134:137], v[66:81]
	ds_read_b64_tr_b16 v[190:191], v150 offset:36864
	ds_read_b64_tr_b16 v[192:193], v150 offset:38912
	v_cvt_pk_bf16_f32 v168, v54, v55
	v_cvt_pk_bf16_f32 v169, v56, v57
	v_cvt_pk_bf16_f32 v170, v58, v59
	v_cvt_pk_bf16_f32 v171, v60, v61
	v_cvt_pk_bf16_f32 v172, v62, v63
	s_waitcnt lgkmcnt(14)
	v_mfma_f32_32x32x16_bf16 v[82:97], v[194:197], v[134:137], v[82:97]
	ds_read_b64_tr_b16 v[194:195], v150 offset:37376
	ds_read_b64_tr_b16 v[196:197], v150 offset:39424
	v_cvt_pk_bf16_f32 v173, v64, v65
	v_permlane32_swap_b32_e32 v166, v168
	v_permlane32_swap_b32_e32 v167, v169
	v_permlane32_swap_b32_e32 v170, v172
	v_permlane32_swap_b32_e32 v171, v173
	s_waitcnt lgkmcnt(6)
	v_mfma_f32_32x32x16_bf16 v[2:17], v[158:161], v[182:185], v[2:17]
	v_max3_f32 v177, v66, v67, v68
	v_max3_f32 v178, v69, v70, v71
	v_max3_f32 v177, v177, v72, v73
	s_waitcnt lgkmcnt(4)
	v_mfma_f32_32x32x16_bf16 v[18:33], v[158:161], v[186:189], v[18:33]
	v_max3_f32 v178, v178, v74, v75
	v_max3_f32 v177, v177, v76, v77
	v_max3_f32 v178, v178, v78, v79
	v_max3_f32 v177, v177, v80, v81
	v_max3_f32 v178, v178, v82, v83
	v_max3_f32 v177, v177, v84, v85
	s_waitcnt lgkmcnt(2)
	v_mfma_f32_32x32x16_bf16 v[2:17], v[162:165], v[190:193], v[2:17]
	v_max3_f32 v178, v178, v86, v87
	v_max3_f32 v177, v177, v88, v89
	v_max3_f32 v178, v178, v90, v91
	v_max3_f32 v177, v177, v92, v93
	v_max3_f32 v178, v178, v94, v95
	v_max3_f32 v177, v177, v96, v97
	s_waitcnt lgkmcnt(0)
	v_mfma_f32_32x32x16_bf16 v[18:33], v[162:165], v[194:197], v[18:33]
	v_max_f32_e32 v177, v177, v178
	v_mov_b32_e32 v178, v177
	s_nop 1
	v_permlane32_swap_b32_e32 v177, v178
	v_max_f32_e32 v177, v177, v178
	v_cmp_ge_f32_e32 vcc, 0x4138aa3b, v177
	s_cmp_eq_u64 vcc, exec
	s_cbranch_scc0 .Lat_rare1_42
; __device__ __forceinline__ void finishSM(f32x16& p0, f32x16& p1, float alpha, float& l_reg, bf16x8& pa0, bf16x8& pa1, bf16x8& pa2, bf16x8& pa3) {
; #pragma unroll
;   for (int r = 0; r < 16; ++r) p1[r] = __builtin_amdgcn_exp2f(p1[r]);
;   float ps = 0;
; #pragma unroll
;   for (int r = 0; r < 16; ++r) ps += p0[r];
; #pragma unroll
;   for (int r = 0; r < 16; ++r) ps += p1[r];
;   { auto rr = __builtin_amdgcn_permlane32_swap(__float_as_uint(ps), __float_as_uint(ps), false, false);
;     ps = __uint_as_float(rr[0]) + __uint_as_float(rr[1]); }
;   l_reg = l_reg * alpha + ps;
;     ...
;   PK4(p0, 0, pa0); PK4(p0, 8, pa1); PK4(p1, 0, pa2); PK4(p1, 8, pa3);
;     ...
; }
; __device__ __forceinline__ void qkt(f32x16& p0, f32x16& p1, const bf16_t* Ks, const bf16x8* qr, const f32x16& negm, int r32, int hi) {
;   p0 = negm; p1 = negm;
; #pragma unroll
;   for (int d0 = 0; d0 < 6; ++d0) { int cb = (d0 * 16 + hi * 8) * 2;
;     bf16x8 b0 = *reinterpret_cast<const bf16x8*>((const char*)Ks + KSWZ(r32, cb));
;     bf16x8 b1 = *reinterpret_cast<const bf16x8*>((const char*)Ks + KSWZ(32 + r32, cb));
;     p0 = __builtin_amdgcn_mfma_f32_32x32x16_bf16(b0, qr[d0], p0, 0, 0, 0);
;     p1 = __builtin_amdgcn_mfma_f32_32x32x16_bf16(b1, qr[d0], p1, 0, 0, 0); }
; }
; __device__ __forceinline__ int v_st(int k, int c) { const int kk = (k & ~0xC) | ((k & 4) << 1) | ((k & 8) >> 1); return ((kk >> 3) * 4 + (c >> 5)) * 512 + ((kk & 7) * 32 + (c & 31)) * 2; }
; __device__ __forceinline__ int v_rd_base(int lane) { return ((lane & 3) << 3) | (((lane >> 2) & 3) << 6) | (((lane >> 4) & 1) << 5) | (((lane >> 5) & 1) << 8); }
; template <int OFF> __device__ __forceinline__ s16x4 tr_read(int vb) {
;   s16x4 r; asm volatile("ds_read_b64_tr_b16 %0, %1 offset:%2" : "=&v"(r) : "v"(vb), "i"(OFF) : "memory"); return r;
; }
; template <int D0> __device__ __forceinline__ void pv_one(f32x16& od, int vb, bf16x8 pa0, bf16x8 pa1, bf16x8 pa2, bf16x8 pa3) {
; __device__ __forceinline__ void attn_item(const bf16_t* __restrict__ Qb, const bf16_t* __restrict__ Kn, const bf16_t* __restrict__ Kr, const bf16_t* __restrict__ Vh,
;                                           const float* __restrict__ csq, bf16_t* __restrict__ Ob, int seq, char* lds) {
;     ...
;   STEP(pB0, pB1, alB, pA0, pA1, alA, NT - 1, false);
;   finishSM(pB0, pB1, alB, l_reg, pa0, pa1, pa2, pa3); SBAR();
;   pv_d0(o, vb0 + sp, pa0, pa1, pa2, pa3);
.Lat_ri_41:
	v_mfma_f32_32x32x16_bf16 v[2:17], v[166:169], v[198:201], v[2:17]
	v_exp_f32_e32 v66, v66
	v_exp_f32_e32 v67, v67
	v_exp_f32_e32 v68, v68
	v_exp_f32_e32 v69, v69
	v_exp_f32_e32 v70, v70
	v_exp_f32_e32 v71, v71
	v_exp_f32_e32 v72, v72
	v_mfma_f32_32x32x16_bf16 v[18:33], v[166:169], v[202:205], v[18:33]
	v_exp_f32_e32 v73, v73
	v_exp_f32_e32 v74, v74
	v_exp_f32_e32 v75, v75
	v_exp_f32_e32 v76, v76
	v_exp_f32_e32 v77, v77
	v_exp_f32_e32 v78, v78
	v_exp_f32_e32 v79, v79
	v_mfma_f32_32x32x16_bf16 v[2:17], v[170:173], v[206:209], v[2:17]
	v_exp_f32_e32 v80, v80
	v_exp_f32_e32 v81, v81
	v_add_f32_e32 v214, v66, v70
	v_add_f32_e32 v215, v67, v71
	v_add_f32_e32 v216, v68, v72
	v_add_f32_e32 v217, v69, v73
	v_add_f32_e32 v214, v214, v74
	v_mfma_f32_32x32x16_bf16 v[18:33], v[170:173], v[210:213], v[18:33]
	v_add_f32_e32 v215, v215, v75
	v_add_f32_e32 v216, v216, v76
	v_add_f32_e32 v217, v217, v77
	v_add_f32_e32 v214, v214, v78
	v_add_f32_e32 v215, v215, v79
	v_add_f32_e32 v216, v216, v80
	v_add_f32_e32 v217, v217, v81
	s_waitcnt vmcnt(0)
	s_cmp_lg_u32 s9, 0
	s_cbranch_scc1 .Lat_rare2_43
.Lat_rr_44:
	s_barrier
	ds_read_b64_tr_b16 v[182:183], v150 offset:49152
	ds_read_b64_tr_b16 v[184:185], v150 offset:51200
	ds_read_b64_tr_b16 v[186:187], v150 offset:49664
	ds_read_b64_tr_b16 v[188:189], v150 offset:51712
	ds_read_b64_tr_b16 v[190:191], v150 offset:53248
	ds_read_b64_tr_b16 v[192:193], v150 offset:55296
	ds_read_b64_tr_b16 v[194:195], v150 offset:53760
	ds_read_b64_tr_b16 v[196:197], v150 offset:55808
	v_exp_f32_e32 v82, v82
	v_exp_f32_e32 v83, v83
	v_exp_f32_e32 v84, v84
	v_exp_f32_e32 v85, v85
	v_exp_f32_e32 v86, v86
	v_exp_f32_e32 v87, v87
	v_exp_f32_e32 v88, v88
	v_exp_f32_e32 v89, v89
	v_exp_f32_e32 v90, v90
	v_exp_f32_e32 v91, v91
	v_exp_f32_e32 v92, v92
	v_exp_f32_e32 v93, v93
	v_exp_f32_e32 v94, v94
	v_exp_f32_e32 v95, v95
	v_exp_f32_e32 v96, v96
	v_exp_f32_e32 v97, v97
	v_cvt_pk_bf16_f32 v158, v66, v67
	v_cvt_pk_bf16_f32 v159, v68, v69
	v_cvt_pk_bf16_f32 v160, v70, v71
	v_cvt_pk_bf16_f32 v161, v72, v73
	v_cvt_pk_bf16_f32 v162, v74, v75
	v_cvt_pk_bf16_f32 v163, v76, v77
	v_cvt_pk_bf16_f32 v164, v78, v79
	v_cvt_pk_bf16_f32 v165, v80, v81
	v_permlane32_swap_b32_e32 v158, v160
	v_permlane32_swap_b32_e32 v159, v161
	v_permlane32_swap_b32_e32 v162, v164
	v_permlane32_swap_b32_e32 v163, v165
	v_add_f32_e32 v214, v214, v82
	v_add_f32_e32 v215, v215, v83
	ds_read_b64_tr_b16 v[198:199], v150 offset:57344
	ds_read_b64_tr_b16 v[200:201], v150 offset:59392
	ds_read_b64_tr_b16 v[202:203], v150 offset:57856
	ds_read_b64_tr_b16 v[204:205], v150 offset:59904
	ds_read_b64_tr_b16 v[206:207], v150 offset:61440
	ds_read_b64_tr_b16 v[208:209], v150 offset:63488
	ds_read_b64_tr_b16 v[210:211], v150 offset:61952
	ds_read_b64_tr_b16 v[212:213], v150 offset:64000
	v_add_f32_e32 v216, v216, v84
	v_add_f32_e32 v217, v217, v85
	v_add_f32_e32 v214, v214, v86
	v_add_f32_e32 v215, v215, v87
	v_add_f32_e32 v216, v216, v88
	v_add_f32_e32 v217, v217, v89
	v_add_f32_e32 v214, v214, v90
	v_add_f32_e32 v215, v215, v91
	v_add_f32_e32 v216, v216, v92
	v_add_f32_e32 v217, v217, v93
	v_add_f32_e32 v214, v214, v94
	v_add_f32_e32 v215, v215, v95
	v_add_f32_e32 v216, v216, v96
	v_add_f32_e32 v217, v217, v97
	v_add_f32_e32 v214, v214, v215
	v_add_f32_e32 v216, v216, v217
	v_add_f32_e32 v214, v214, v216
	v_add_f32_e32 v174, v174, v214
	v_cvt_pk_bf16_f32 v166, v82, v83
	v_cvt_pk_bf16_f32 v167, v84, v85
	v_cvt_pk_bf16_f32 v168, v86, v87
	v_cvt_pk_bf16_f32 v169, v88, v89
	v_cvt_pk_bf16_f32 v170, v90, v91
	v_cvt_pk_bf16_f32 v171, v92, v93
	v_cvt_pk_bf16_f32 v172, v94, v95
	v_cvt_pk_bf16_f32 v173, v96, v97
	v_permlane32_swap_b32_e32 v166, v168
	v_permlane32_swap_b32_e32 v167, v169
	v_permlane32_swap_b32_e32 v170, v172
	v_permlane32_swap_b32_e32 v171, v173
	s_waitcnt lgkmcnt(14)
	v_mfma_f32_32x32x16_bf16 v[2:17], v[158:161], v[182:185], v[2:17]
	s_waitcnt lgkmcnt(12)
	v_mfma_f32_32x32x16_bf16 v[18:33], v[158:161], v[186:189], v[18:33]
	s_waitcnt lgkmcnt(10)
	v_mfma_f32_32x32x16_bf16 v[2:17], v[162:165], v[190:193], v[2:17]
	s_waitcnt lgkmcnt(8)
	v_mfma_f32_32x32x16_bf16 v[18:33], v[162:165], v[194:197], v[18:33]
	s_waitcnt lgkmcnt(6)
	v_mfma_f32_32x32x16_bf16 v[2:17], v[166:169], v[198:201], v[2:17]
	s_waitcnt lgkmcnt(4)
	v_mfma_f32_32x32x16_bf16 v[18:33], v[166:169], v[202:205], v[18:33]
	s_waitcnt lgkmcnt(2)
	v_mfma_f32_32x32x16_bf16 v[2:17], v[170:173], v[206:209], v[2:17]
	s_waitcnt lgkmcnt(0)
	v_mfma_f32_32x32x16_bf16 v[18:33], v[170:173], v[210:213], v[18:33]
	s_waitcnt vmcnt(0)
	s_cmp_lg_u32 s9, 0
	s_cbranch_scc1 .Lat_rare2_46
; __device__ __forceinline__ unsigned f2bf(float f) { unsigned u = __builtin_bit_cast(unsigned, f); return (u + 0x7fffu + ((u >> 16) & 1u)) >> 16; }
; __device__ __forceinline__ int crow(int r, int hi) { return (r & 3) + 8 * (r >> 2) + 4 * hi; }
; __device__ __forceinline__ void attn_item(const bf16_t* __restrict__ Qb, const bf16_t* __restrict__ Kn, const bf16_t* __restrict__ Kr, const bf16_t* __restrict__ Vh,
;                                           const float* __restrict__ csq, bf16_t* __restrict__ Ob, int seq, char* lds) {
;     ...
;   __builtin_amdgcn_s_setprio(0);
;   if (hi == 0) li_l[r32] = l_reg; asm volatile("s_waitcnt lgkmcnt(0)" ::: "memory");
;   float rli[16];
; #pragma unroll
;   for (int r = 0; r < 16; ++r) rli[r] = __builtin_amdgcn_rcpf(li_l[crow(r, hi)]);
;   bf16_t* Ow = Ob + (long)(wid * QBLK) * DM;
; #pragma unroll
;   for (int r = 0; r < 16; ++r) { int orow = crow(r, hi);
; #pragma unroll
;     for (int d0 = 0; d0 < 2; ++d0) Ow[(long)orow * DM + d0 * 32 + r32] = (bf16_t)f2bf(o[d0][r] * rli[r]); }
; __global__ void __launch_bounds__(512, 2) mega(Args a_unused) {
;     ...
;             if constexpr (PHMASK & 512) for (int rep = 0; rep <= DUP_ATT; ++rep) for (int it = C.vcu; it < NB * NH * (SEQ / 256); it += C.G) { const int bh = it >> 5, qb = it & 31; const int b = bh >> 3, hh = bh & 7;
.Lat_rr_47:
	s_barrier
	s_setprio 0
	s_nop 7
	s_nop 7
	v_mov_b32_e32 v177, v174
	s_nop 1
	v_permlane32_swap_b32_e32 v174, v177
	v_add_f32_e32 v174, v174, v177
	s_mov_b32 exec_hi, 0
	ds_write_b32 v175, v174
	s_mov_b64 exec, -1
	s_waitcnt lgkmcnt(0)
	ds_read_b128 v[182:185], v176 offset:0
	ds_read_b128 v[186:189], v176 offset:32
	ds_read_b128 v[190:193], v176 offset:64
	ds_read_b128 v[194:197], v176 offset:96
	v_and_b32_e32 v1, 63, v180
	v_and_b32_e32 v178, 31, v1
	v_lshrrev_b32_e32 v179, 5, v1
	s_lshl_b32 s30, s29, 16
	v_lshlrev_b32_e32 v177, 13, v179
	v_add_u32_e32 v177, s30, v177
	v_lshl_add_u32 v177, v178, 1, v177
	s_waitcnt lgkmcnt(0)
	v_rcp_f32_e32 v182, v182
	v_rcp_f32_e32 v183, v183
	v_rcp_f32_e32 v184, v184
	v_rcp_f32_e32 v185, v185
	v_rcp_f32_e32 v186, v186
	v_rcp_f32_e32 v187, v187
	v_rcp_f32_e32 v188, v188
	v_rcp_f32_e32 v189, v189
	v_rcp_f32_e32 v190, v190
	v_rcp_f32_e32 v191, v191
	v_rcp_f32_e32 v192, v192
	v_rcp_f32_e32 v193, v193
	v_rcp_f32_e32 v194, v194
	v_rcp_f32_e32 v195, v195
	v_rcp_f32_e32 v196, v196
	v_rcp_f32_e32 v197, v197
	s_nop 0
	v_add_u32_e32 v198, 0, v177
	v_add_u32_e32 v199, 4096, v177
	v_add_u32_e32 v200, 16384, v177
	v_add_u32_e32 v201, 20480, v177
	v_add_u32_e32 v202, 32768, v177
	v_add_u32_e32 v203, 36864, v177
	v_add_u32_e32 v204, 49152, v177
	v_add_u32_e32 v205, 53248, v177
	v_mul_f32_e32 v2, v2, v182
	v_bfe_u32 v1, v2, 16, 1
	v_add3_u32 v2, v2, v1, s25
	global_store_short_d16_hi v198, v2, s[26:27] offset:0
	v_mul_f32_e32 v18, v18, v182
	v_bfe_u32 v1, v18, 16, 1
	v_add3_u32 v18, v18, v1, s25
	global_store_short_d16_hi v198, v18, s[26:27] offset:64
	v_mul_f32_e32 v3, v3, v183
	v_bfe_u32 v1, v3, 16, 1
	v_add3_u32 v3, v3, v1, s25
	global_store_short_d16_hi v198, v3, s[26:27] offset:2048
	v_mul_f32_e32 v19, v19, v183
	v_bfe_u32 v1, v19, 16, 1
	v_add3_u32 v19, v19, v1, s25
	global_store_short_d16_hi v198, v19, s[26:27] offset:2112
	v_mul_f32_e32 v4, v4, v184
	v_bfe_u32 v1, v4, 16, 1
	v_add3_u32 v4, v4, v1, s25
	global_store_short_d16_hi v199, v4, s[26:27] offset:0
	v_mul_f32_e32 v20, v20, v184
	v_bfe_u32 v1, v20, 16, 1
	v_add3_u32 v20, v20, v1, s25
	global_store_short_d16_hi v199, v20, s[26:27] offset:64
	v_mul_f32_e32 v5, v5, v185
	v_bfe_u32 v1, v5, 16, 1
	v_add3_u32 v5, v5, v1, s25
	global_store_short_d16_hi v199, v5, s[26:27] offset:2048
	v_mul_f32_e32 v21, v21, v185
	v_bfe_u32 v1, v21, 16, 1
	v_add3_u32 v21, v21, v1, s25
	global_store_short_d16_hi v199, v21, s[26:27] offset:2112
	v_mul_f32_e32 v6, v6, v186
	v_bfe_u32 v1, v6, 16, 1
	v_add3_u32 v6, v6, v1, s25
	global_store_short_d16_hi v200, v6, s[26:27] offset:0
	v_mul_f32_e32 v22, v22, v186
	v_bfe_u32 v1, v22, 16, 1
	v_add3_u32 v22, v22, v1, s25
	global_store_short_d16_hi v200, v22, s[26:27] offset:64
	v_mul_f32_e32 v7, v7, v187
	v_bfe_u32 v1, v7, 16, 1
	v_add3_u32 v7, v7, v1, s25
	global_store_short_d16_hi v200, v7, s[26:27] offset:2048
	v_mul_f32_e32 v23, v23, v187
	v_bfe_u32 v1, v23, 16, 1
	v_add3_u32 v23, v23, v1, s25
	global_store_short_d16_hi v200, v23, s[26:27] offset:2112
	v_mul_f32_e32 v8, v8, v188
	v_bfe_u32 v1, v8, 16, 1
	v_add3_u32 v8, v8, v1, s25
	global_store_short_d16_hi v201, v8, s[26:27] offset:0
	v_mul_f32_e32 v24, v24, v188
	v_bfe_u32 v1, v24, 16, 1
	v_add3_u32 v24, v24, v1, s25
	global_store_short_d16_hi v201, v24, s[26:27] offset:64
	v_mul_f32_e32 v9, v9, v189
	v_bfe_u32 v1, v9, 16, 1
	v_add3_u32 v9, v9, v1, s25
	global_store_short_d16_hi v201, v9, s[26:27] offset:2048
	v_mul_f32_e32 v25, v25, v189
	v_bfe_u32 v1, v25, 16, 1
	v_add3_u32 v25, v25, v1, s25
	global_store_short_d16_hi v201, v25, s[26:27] offset:2112
	v_mul_f32_e32 v10, v10, v190
	v_bfe_u32 v1, v10, 16, 1
	v_add3_u32 v10, v10, v1, s25
	global_store_short_d16_hi v202, v10, s[26:27] offset:0
	v_mul_f32_e32 v26, v26, v190
	v_bfe_u32 v1, v26, 16, 1
	v_add3_u32 v26, v26, v1, s25
	global_store_short_d16_hi v202, v26, s[26:27] offset:64
	v_mul_f32_e32 v11, v11, v191
	v_bfe_u32 v1, v11, 16, 1
	v_add3_u32 v11, v11, v1, s25
	global_store_short_d16_hi v202, v11, s[26:27] offset:2048
	v_mul_f32_e32 v27, v27, v191
	v_bfe_u32 v1, v27, 16, 1
	v_add3_u32 v27, v27, v1, s25
	global_store_short_d16_hi v202, v27, s[26:27] offset:2112
	v_mul_f32_e32 v12, v12, v192
	v_bfe_u32 v1, v12, 16, 1
	v_add3_u32 v12, v12, v1, s25
	global_store_short_d16_hi v203, v12, s[26:27] offset:0
	v_mul_f32_e32 v28, v28, v192
	v_bfe_u32 v1, v28, 16, 1
	v_add3_u32 v28, v28, v1, s25
	global_store_short_d16_hi v203, v28, s[26:27] offset:64
	v_mul_f32_e32 v13, v13, v193
	v_bfe_u32 v1, v13, 16, 1
	v_add3_u32 v13, v13, v1, s25
	global_store_short_d16_hi v203, v13, s[26:27] offset:2048
	v_mul_f32_e32 v29, v29, v193
	v_bfe_u32 v1, v29, 16, 1
	v_add3_u32 v29, v29, v1, s25
	global_store_short_d16_hi v203, v29, s[26:27] offset:2112
	v_mul_f32_e32 v14, v14, v194
	v_bfe_u32 v1, v14, 16, 1
	v_add3_u32 v14, v14, v1, s25
	global_store_short_d16_hi v204, v14, s[26:27] offset:0
	v_mul_f32_e32 v30, v30, v194
	v_bfe_u32 v1, v30, 16, 1
	v_add3_u32 v30, v30, v1, s25
	global_store_short_d16_hi v204, v30, s[26:27] offset:64
	v_mul_f32_e32 v15, v15, v195
	v_bfe_u32 v1, v15, 16, 1
	v_add3_u32 v15, v15, v1, s25
	global_store_short_d16_hi v204, v15, s[26:27] offset:2048
	v_mul_f32_e32 v31, v31, v195
	v_bfe_u32 v1, v31, 16, 1
	v_add3_u32 v31, v31, v1, s25
	global_store_short_d16_hi v204, v31, s[26:27] offset:2112
	v_mul_f32_e32 v16, v16, v196
	v_bfe_u32 v1, v16, 16, 1
	v_add3_u32 v16, v16, v1, s25
	global_store_short_d16_hi v205, v16, s[26:27] offset:0
	v_mul_f32_e32 v32, v32, v196
	v_bfe_u32 v1, v32, 16, 1
	v_add3_u32 v32, v32, v1, s25
	global_store_short_d16_hi v205, v32, s[26:27] offset:64
	v_mul_f32_e32 v17, v17, v197
	v_bfe_u32 v1, v17, 16, 1
	v_add3_u32 v17, v17, v1, s25
	global_store_short_d16_hi v205, v17, s[26:27] offset:2048
	v_mul_f32_e32 v33, v33, v197
	v_bfe_u32 v1, v33, 16, 1
	v_add3_u32 v33, v33, v1, s25
	global_store_short_d16_hi v205, v33, s[26:27] offset:2112
	s_add_i32 s28, s28, s92
	s_cmpk_lt_i32 s28, 0x400
	s_cbranch_scc1 .Lat_item
	s_branch .Lat_done
; template <bool FIRST> __device__ __forceinline__ void partialSM(f32x16& p0, f32x16& p1, float& mhat, f32x16& negm, float& alpha) {
;     ...
;   if (!FIRST && __builtin_expect(__all(pmax <= THRL), 1)) { alpha = 1.f; }
;   else { const float d = FIRST ? pmax : fmaxf(pmax, 0.f); mhat += d; alpha = FIRST ? 1.f : __builtin_amdgcn_exp2f(-d);
; #pragma unroll
;     for (int r = 0; r < 16; ++r) { p0[r] -= d; p1[r] -= d; }
; #pragma unroll
;     for (int r = 0; r < 16; ++r) negm[r] = -mhat; }
.Lat_tramp187:
	s_branch .LBB0_187
.Lat_rare1_2:
	v_max_f32_e32 v177, 0, v177
	v_exp_f32_e64 v178, -v177
	v_add_f32_e32 v151, v151, v177
	v_sub_f32_e32 v66, v66, v177
	v_sub_f32_e32 v67, v67, v177
	v_sub_f32_e32 v68, v68, v177
	v_sub_f32_e32 v69, v69, v177
	v_sub_f32_e32 v70, v70, v177
	v_sub_f32_e32 v71, v71, v177
	v_sub_f32_e32 v72, v72, v177
	v_sub_f32_e32 v73, v73, v177
	v_sub_f32_e32 v74, v74, v177
	v_sub_f32_e32 v75, v75, v177
	v_sub_f32_e32 v76, v76, v177
	v_sub_f32_e32 v77, v77, v177
	v_sub_f32_e32 v78, v78, v177
	v_sub_f32_e32 v79, v79, v177
	v_sub_f32_e32 v80, v80, v177
	v_sub_f32_e32 v81, v81, v177
	v_sub_f32_e32 v82, v82, v177
	v_sub_f32_e32 v83, v83, v177
	v_sub_f32_e32 v84, v84, v177
	v_sub_f32_e32 v85, v85, v177
	v_sub_f32_e32 v86, v86, v177
	v_sub_f32_e32 v87, v87, v177
	v_sub_f32_e32 v88, v88, v177
	v_sub_f32_e32 v89, v89, v177
	v_sub_f32_e32 v90, v90, v177
	v_sub_f32_e32 v91, v91, v177
	v_sub_f32_e32 v92, v92, v177
	v_sub_f32_e32 v93, v93, v177
	v_sub_f32_e32 v94, v94, v177
	v_sub_f32_e32 v95, v95, v177
	v_sub_f32_e32 v96, v96, v177
	v_sub_f32_e32 v97, v97, v177
	v_xor_b32_e32 v98, 0x80000000, v151
	v_mov_b32_e32 v99, v98
	v_mov_b32_e32 v100, v98
	v_mov_b32_e32 v101, v98
	v_mov_b32_e32 v102, v98
	v_mov_b32_e32 v103, v98
	v_mov_b32_e32 v104, v98
	v_mov_b32_e32 v105, v98
	v_mov_b32_e32 v106, v98
	v_mov_b32_e32 v107, v98
	v_mov_b32_e32 v108, v98
	v_mov_b32_e32 v109, v98
	v_mov_b32_e32 v110, v98
	v_mov_b32_e32 v111, v98
	v_mov_b32_e32 v112, v98
	v_mov_b32_e32 v113, v98
	v_mul_f32_e32 v174, v174, v178
	s_mov_b32 exec_hi, 0
	ds_write_b32 v175, v178 offset:128
	s_mov_b64 exec, -1
	s_mov_b32 s9, 1
	s_nop 3
	s_branch .Lat_ri_1
.Lat_rare2_3:
	s_nop 15
	s_waitcnt lgkmcnt(0)
	ds_read_b128 v[198:201], v176 offset:128
	ds_read_b128 v[202:205], v176 offset:160
	ds_read_b128 v[206:209], v176 offset:192
	ds_read_b128 v[210:213], v176 offset:224
	s_waitcnt lgkmcnt(0)
	v_mul_f32_e32 v2, v2, v198
	v_mul_f32_e32 v3, v3, v199
	v_mul_f32_e32 v4, v4, v200
	v_mul_f32_e32 v5, v5, v201
	v_mul_f32_e32 v6, v6, v202
	v_mul_f32_e32 v7, v7, v203
	v_mul_f32_e32 v8, v8, v204
	v_mul_f32_e32 v9, v9, v205
	v_mul_f32_e32 v10, v10, v206
	v_mul_f32_e32 v11, v11, v207
	v_mul_f32_e32 v12, v12, v208
	v_mul_f32_e32 v13, v13, v209
	v_mul_f32_e32 v14, v14, v210
	v_mul_f32_e32 v15, v15, v211
	v_mul_f32_e32 v16, v16, v212
	v_mul_f32_e32 v17, v17, v213
	v_mul_f32_e32 v18, v18, v198
	v_mul_f32_e32 v19, v19, v199
	v_mul_f32_e32 v20, v20, v200
	v_mul_f32_e32 v21, v21, v201
	v_mul_f32_e32 v22, v22, v202
	v_mul_f32_e32 v23, v23, v203
	v_mul_f32_e32 v24, v24, v204
	v_mul_f32_e32 v25, v25, v205
	v_mul_f32_e32 v26, v26, v206
	v_mul_f32_e32 v27, v27, v207
	v_mul_f32_e32 v28, v28, v208
	v_mul_f32_e32 v29, v29, v209
	v_mul_f32_e32 v30, v30, v210
	v_mul_f32_e32 v31, v31, v211
	v_mul_f32_e32 v32, v32, v212
	v_mul_f32_e32 v33, v33, v213
	s_mov_b32 s9, 0
	s_nop 3
	s_branch .Lat_rr_4
.Lat_rare1_6:
	v_max_f32_e32 v177, 0, v177
	v_exp_f32_e64 v178, -v177
	v_add_f32_e32 v151, v151, v177
	v_sub_f32_e32 v34, v34, v177
	v_sub_f32_e32 v35, v35, v177
	v_sub_f32_e32 v36, v36, v177
	v_sub_f32_e32 v37, v37, v177
	v_sub_f32_e32 v38, v38, v177
	v_sub_f32_e32 v39, v39, v177
	v_sub_f32_e32 v40, v40, v177
	v_sub_f32_e32 v41, v41, v177
	v_sub_f32_e32 v42, v42, v177
	v_sub_f32_e32 v43, v43, v177
	v_sub_f32_e32 v44, v44, v177
	v_sub_f32_e32 v45, v45, v177
	v_sub_f32_e32 v46, v46, v177
	v_sub_f32_e32 v47, v47, v177
	v_sub_f32_e32 v48, v48, v177
	v_sub_f32_e32 v49, v49, v177
	v_sub_f32_e32 v50, v50, v177
	v_sub_f32_e32 v51, v51, v177
	v_sub_f32_e32 v52, v52, v177
	v_sub_f32_e32 v53, v53, v177
	v_sub_f32_e32 v54, v54, v177
	v_sub_f32_e32 v55, v55, v177
	v_sub_f32_e32 v56, v56, v177
	v_sub_f32_e32 v57, v57, v177
	v_sub_f32_e32 v58, v58, v177
	v_sub_f32_e32 v59, v59, v177
	v_sub_f32_e32 v60, v60, v177
	v_sub_f32_e32 v61, v61, v177
	v_sub_f32_e32 v62, v62, v177
	v_sub_f32_e32 v63, v63, v177
	v_sub_f32_e32 v64, v64, v177
	v_sub_f32_e32 v65, v65, v177
	v_xor_b32_e32 v98, 0x80000000, v151
	v_mov_b32_e32 v99, v98
	v_mov_b32_e32 v100, v98
	v_mov_b32_e32 v101, v98
	v_mov_b32_e32 v102, v98
	v_mov_b32_e32 v103, v98
	v_mov_b32_e32 v104, v98
	v_mov_b32_e32 v105, v98
	v_mov_b32_e32 v106, v98
	v_mov_b32_e32 v107, v98
	v_mov_b32_e32 v108, v98
	v_mov_b32_e32 v109, v98
	v_mov_b32_e32 v110, v98
	v_mov_b32_e32 v111, v98
	v_mov_b32_e32 v112, v98
	v_mov_b32_e32 v113, v98
	v_mul_f32_e32 v174, v174, v178
	s_mov_b32 exec_hi, 0
	ds_write_b32 v175, v178 offset:128
	s_mov_b64 exec, -1
	s_mov_b32 s9, 1
	s_nop 3
	s_branch .Lat_ri_5

; __device__ __forceinline__ void conv_tile(const Ctx& C, const bf16_t* uconv, bf16_t* y, const float* dw, const float* db, const float* lg, const float* lb, int tile) {
;     bf16_t* U = (bf16_t*)C.lds;
;     float* O = (float*)(C.lds + 94 * 512);
;     const int tid = C.tid; const int row0 = tile * 64; const int b = row0 >> 13, l0 = row0 & 8191;
;     __syncthreads();
; #pragma unroll 6
;     for (int i = tid; i < 94 * 32; i += 512) { const int r = i >> 5, cc = i & 31; const int l = l0 - 15 + r;
;         u32x4 v = (u32x4){0u, 0u, 0u, 0u}; if (l >= 0 && l < SEQ) v = *(const u32x4*)(uconv + (size_t)(b * SEQ + l) * 256 + cc * 8);
;         *(u32x4*)(U + r * 256 + cc * 8) = v; }
;     __syncthreads();
;     { const int c = tid & 255, phh = tid >> 8;
;       float w[31], acc[32];
; #pragma unroll
;       for (int j = 0; j < 31; ++j) w[j] = dw[j * 256 + c];
;       const float bb = db[c];
; #pragma unroll
;       for (int p = 0; p < 32; ++p) acc[p] = bb;
; #pragma unroll
;       for (int q = 0; q < 62; ++q) { const float val = bf2f(U[(32 * phh + q) * 256 + c]);
; #pragma unroll
;           for (int p = 0; p < 32; ++p) if (q - p >= 0 && q - p <= 30) acc[p] += w[q - p] * val; }
; #pragma unroll
;       for (int p = 0; p < 32; ++p) O[(32 * phh + p) * 260 + c] = acc[p]; }
;     __syncthreads();
; __global__ void __launch_bounds__(512, 2) mega(Args a_unused) {
;     ...
;         PH_BEGIN
;             if constexpr (PHMASK & 1024) for (int t = C.vcu; t < MTOK / 64; t += C.G)
;                 conv_tile(C, UC, YB, GIN(a, 12) + ly * 31 * 256, GIN(a, 13) + ly * 256, GIN(a, 14) + ly * 256, GIN(a, 15) + ly * 256, t);
.Lat_done:
.LBB0_707:
	s_mov_b64 s[8:9], s[84:85]
	s_load_dword s0, s[8:9], 0x120
	s_waitcnt lgkmcnt(0)
	s_cmp_lt_i32 s24, s0
	s_cbranch_scc1 .LBB0_736
	s_load_dword s0, s[8:9], 0x124
	s_waitcnt lgkmcnt(0)
	s_cmp_ge_i32 s24, s0
	s_cbranch_scc1 .LBB0_736
	v_readlane_b32 s0, v255, 51
	v_mov_b32_e32 v1, v180
	v_readlane_b32 s1, v255, 52
	s_andn2_b64 vcc, exec, s[0:1]
	v_readfirstlane_b32 s0, v1
	s_cbranch_vccnz .LBB0_736
	s_load_dwordx8 s[36:43], s[8:9], 0x60
	s_load_dwordx4 s[16:19], s[8:9], 0x110
	s_mul_i32 s60, s81, 0x1f00
	s_lshl_b64 s[6:7], s[60:61], 2
	v_lshlrev_b32_e32 v2, 4, v1
	s_waitcnt lgkmcnt(0)
	s_add_u32 s6, s36, s6
	s_addc_u32 s7, s37, s7
	s_lshl_b32 s60, s81, 8
	s_lshl_b64 s[8:9], s[60:61], 2
	s_add_u32 s10, s38, s8
	v_and_b32_e32 v2, 0x1f0, v2
	v_mov_b32_e32 v3, v0
	s_addc_u32 s11, s39, s9
	v_lshl_add_u64 v[4:5], s[18:19], 0, v[2:3]
	s_mov_b64 s[18:19], 0x19e00000
	s_add_u32 s12, s40, s8
	v_lshl_add_u64 v[14:15], v[4:5], 0, s[18:19]
	v_add_u32_e32 v80, 0, v2
	v_lshlrev_b32_sdwa v2, v157, v1 dst_sel:DWORD dst_unused:UNUSED_PAD src0_sel:DWORD src1_sel:BYTE_0
	v_ashrrev_i32_e32 v4, 8, v1
	s_addc_u32 s13, s41, s9
	v_lshl_add_u64 v[16:17], s[6:7], 0, v[2:3]
	v_lshl_add_u64 v[72:73], s[10:11], 0, v[2:3]
	v_mul_i32_i24_e32 v3, 0x2080, v4
	v_and_b32_e32 v6, 63, v1
	s_add_u32 s14, s42, s8
	v_lshlrev_b32_e32 v3, 2, v3
	s_addc_u32 s15, s43, s9
	v_add3_u32 v81, 0, v3, v2
	v_add3_u32 v82, 0, v2, v3
	v_lshlrev_b32_e32 v2, 4, v6
	v_mov_b32_e32 v3, v0
	v_lshl_add_u64 v[74:75], s[12:13], 0, v[2:3]
	v_lshl_add_u64 v[76:77], s[14:15], 0, v[2:3]
	v_and_b32_e32 v3, 64, v156
	v_add_u32_e32 v3, 64, v3
	v_xor_b32_e32 v5, 1, v156
	v_cmp_lt_i32_e32 vcc, v5, v3
	s_mov_b64 s[6:7], 0x1000
	v_lshl_add_u64 v[18:19], v[16:17], 0, s[6:7]
	v_cndmask_b32_e32 v5, v156, v5, vcc
	v_lshlrev_b32_e32 v84, 2, v5
	v_xor_b32_e32 v5, 2, v156
	v_cmp_lt_i32_e32 vcc, v5, v3
	s_mov_b64 s[6:7], 0x1400
	v_lshl_add_u64 v[20:21], v[16:17], 0, s[6:7]
	v_cndmask_b32_e32 v5, v156, v5, vcc
	s_mov_b64 s[6:7], 0x1800
	v_lshlrev_b32_e32 v85, 2, v5
	v_xor_b32_e32 v5, 4, v156
	v_lshl_add_u64 v[22:23], v[16:17], 0, s[6:7]
	s_mov_b64 s[6:7], 0x1c00
	v_cmp_lt_i32_e32 vcc, v5, v3
	v_lshl_add_u64 v[24:25], v[16:17], 0, s[6:7]
	s_mov_b64 s[6:7], 0x2400
	v_cndmask_b32_e32 v5, v156, v5, vcc
	v_lshl_add_u64 v[28:29], v[16:17], 0, s[6:7]
	s_mov_b64 s[6:7], 0x2800
	v_lshlrev_b32_e32 v86, 2, v5
	v_xor_b32_e32 v5, 8, v156
	v_lshl_add_u64 v[30:31], v[16:17], 0, s[6:7]
	s_mov_b64 s[6:7], 0x2c00
	v_cmp_lt_i32_e32 vcc, v5, v3
	v_lshl_add_u64 v[32:33], v[16:17], 0, s[6:7]
	s_mov_b64 s[6:7], 0x3000
	v_cndmask_b32_e32 v5, v156, v5, vcc
	v_lshl_add_u64 v[34:35], v[16:17], 0, s[6:7]
	s_mov_b64 s[6:7], 0x3400
	v_lshlrev_b32_e32 v87, 2, v5
	v_xor_b32_e32 v5, 16, v156
	v_lshl_add_u64 v[36:37], v[16:17], 0, s[6:7]
	s_mov_b64 s[6:7], 0x3800
	v_cmp_lt_i32_e32 vcc, v5, v3
	v_lshl_add_u64 v[38:39], v[16:17], 0, s[6:7]
	s_mov_b64 s[6:7], 0x3c00
	v_cndmask_b32_e32 v5, v156, v5, vcc
	v_lshl_add_u64 v[40:41], v[16:17], 0, s[6:7]
	s_mov_b64 s[6:7], 0x4000
	v_lshlrev_b32_e32 v88, 2, v5
	v_xor_b32_e32 v5, 32, v156
	v_lshl_add_u64 v[42:43], v[16:17], 0, s[6:7]
	s_mov_b64 s[6:7], 0x4400
	v_cmp_lt_i32_e32 vcc, v5, v3
	v_lshl_add_u64 v[44:45], v[16:17], 0, s[6:7]
	s_mov_b64 s[6:7], 0x4800
	v_cndmask_b32_e32 v3, v156, v5, vcc
	v_lshl_add_u64 v[46:47], v[16:17], 0, s[6:7]
	s_mov_b64 s[6:7], 0x4c00
	v_lshlrev_b32_e32 v89, 2, v3
	v_lshlrev_b32_sdwa v3, v155, v1 dst_sel:DWORD dst_unused:UNUSED_PAD src0_sel:DWORD src1_sel:BYTE_0
	v_lshl_add_u64 v[48:49], v[16:17], 0, s[6:7]
	s_mov_b64 s[6:7], 0x5000
	v_lshl_or_b32 v3, v4, 14, v3
	v_lshl_add_u64 v[50:51], v[16:17], 0, s[6:7]
	s_mov_b64 s[6:7], 0x5400
	v_add_u32_e32 v90, 0, v3
	v_max_i32_e32 v3, 0x9c0, v1
	v_lshl_add_u64 v[52:53], v[16:17], 0, s[6:7]
	s_mov_b64 s[6:7], 0x5800
	v_sub_u32_e32 v3, v3, v1
	v_lshl_add_u64 v[54:55], v[16:17], 0, s[6:7]
	s_mov_b64 s[6:7], 0x5c00
	v_add_u32_e32 v3, 0x1ff, v3
	v_lshl_add_u64 v[56:57], v[16:17], 0, s[6:7]
	s_mov_b64 s[6:7], 0x6000
	v_lshrrev_b32_e32 v4, 9, v3
	v_lshl_add_u64 v[58:59], v[16:17], 0, s[6:7]
	s_mov_b64 s[6:7], 0x6400
	v_mul_hi_u32 v5, v4, s69
	v_lshl_add_u64 v[60:61], v[16:17], 0, s[6:7]
	s_mov_b64 s[6:7], 0x6800
	s_ashr_i32 s0, s0, 3
	v_mul_u32_u24_e32 v5, 6, v5
	v_lshl_add_u64 v[62:63], v[16:17], 0, s[6:7]
	s_mov_b64 s[6:7], 0x6c00
	s_and_b32 s22, s0, -8
	s_or_b32 s23, s0, 7
	v_sub_u32_e32 v4, v4, v5
	s_lshr_b32 s0, s0, 3
	v_lshl_add_u64 v[64:65], v[16:17], 0, s[6:7]
	s_mov_b64 s[6:7], 0x7000
	v_add_u32_e32 v4, 1, v4
	s_mulk_i32 s0, 0x2080
	s_movk_i32 s1, 0xbc0
	v_lshl_add_u64 v[66:67], v[16:17], 0, s[6:7]
	s_mov_b64 s[6:7], 0x7400
	v_cmp_ne_u32_e64 s[10:11], 6, v4
	s_add_i32 s0, s0, 0
	v_cmp_gt_i32_e64 s[8:9], s1, v1
	v_lshl_add_u64 v[68:69], v[16:17], 0, s[6:7]
	s_mov_b64 s[6:7], 0x7800
	v_cndmask_b32_e64 v91, 0, v4, s[10:11]
	s_movk_i32 s1, 0x9ff
	v_lshlrev_b32_e32 v4, 3, v6
	v_mov_b32_e32 v5, v0
	s_add_i32 s0, s0, 0xbc00
	v_lshl_add_u64 v[26:27], v[16:17], 0, s[90:91]
	v_lshl_add_u64 v[70:71], v[16:17], 0, s[6:7]
	v_add_u32_e32 v83, 0xbc00, v82
	v_cmp_lt_u32_e64 s[12:13], s1, v3
	v_lshl_add_u64 v[78:79], s[16:17], 0, v[4:5]
	v_add_u32_e32 v92, s0, v2
	v_readlane_b32 s25, v255, 19
	v_readlane_b32 s26, v255, 49
